# SwiGLU epilogues rewritten by hand: row scale folded into the exp argument and final product, cheap u64->f32 stat conversion, packed f32 ops, no dead address math (48 instead of ~70 VALU per row); f32
# speedup vs baseline: 1.0089x; 1.0065x over previous
; __device__ __forceinline__ float ss_scale(const u64* ss, int row) { return __builtin_amdgcn_rsqf((float)ss[row] * (1.f / 4294967296.f / 1024.f) + EPS); }
; __device__ __forceinline__ unsigned pkbf(float lo, float hi) { typedef __bf16 bf2_t __attribute__((ext_vector_type(2))); f32x2 v = {lo, hi}; bf2_t b = __builtin_convertvector(v, bf2_t); return __builtin_bit_cast(unsigned, b); }
; __device__ __forceinline__ float silu_f(float g) { return g * __builtin_amdgcn_rcpf(1.f + __builtin_amdgcn_exp2f(-g * LOG2E)); }
;     __device__ __forceinline__ void operator()(const f32x4 (&acc)[2][2][4][2], const pg8::Unit& u, int wr, int wc, int fr, int fq) const {
;         const int row0 = u.pm * 256 + wr * 64 + fr, col0 = u.pn * 128 + wc * 32 + 8 * fq;
; #pragma unroll
;         for (int ai = 0; ai < 2; ++ai)
; #pragma unroll
;             for (int m = 0; m < 4; ++m) {
;                 const int row = row0 + ai * 128 + m * 16;
;                 float s = ss_scale(ss, row);
;                 if constexpr (NN) s *= __builtin_amdgcn_rsqf(s * s * (float)ssw[row] * (1.f / 4294967296.f / 1024.f) + EPS);
;                 float a[8];
; #pragma unroll
;                 for (int n = 0; n < 2; ++n)
; #pragma unroll
;                     for (int i = 0; i < 4; ++i) { const float g = acc[ai][0][m][n][i] * s, uu = acc[ai][1][m][n][i] * s; a[4 * n + i] = silu_f(g) * uu; }
;                 u32x4 w; w.x = pkbf(a[0], a[1]); w.y = pkbf(a[2], a[3]); w.z = pkbf(a[4], a[5]); w.w = pkbf(a[6], a[7]);
;                 *(u32x4*)(O + (size_t)row * FF + col0) = w;
.LBB0_282:
	v_lshl_add_u32 v144, s22, 8, v152
	v_mov_b32_e32 v145, 0
	v_lshl_add_u64 v[150:151], v[144:145], 3, s[6:7]
	global_load_dwordx2 v[176:177], v[150:151], off
	global_load_dwordx2 v[178:179], v[150:151], off offset:128
	global_load_dwordx2 v[180:181], v[150:151], off offset:256
	global_load_dwordx2 v[182:183], v[150:151], off offset:384
	global_load_dwordx2 v[184:185], v[150:151], off offset:1024
	global_load_dwordx2 v[186:187], v[150:151], off offset:1152
	global_load_dwordx2 v[188:189], v[150:151], off offset:1280
	global_load_dwordx2 v[190:191], v[150:151], off offset:1408
	v_lshl_or_b32 v148, s53, 7, v153
	v_mul_u32_u24_e32 v146, s52, v144
	v_lshl_add_u32 v146, v148, 1, v146
	v_mov_b32_e32 v147, 0
	v_lshl_add_u64 v[146:147], v[146:147], 0, s[8:9]
	v_mov_b32_e32 v164, 1.0
	v_mov_b32_e32 v165, 1.0
	s_andn2_b64 vcc, exec, s[2:3]
	s_mov_b64 s[2:3], -1
	s_mov_b32 s101, 0
	s_waitcnt vmcnt(7)
	v_cvt_f32_u32_e32 v166, v177
	v_cvt_f32_u32_e32 v167, v176
	v_fmamk_f32 v166, v166, 0x4f800000, v167
	v_fmamk_f32 v166, v166, 0x2a800000, v159
	v_rsq_f32_e32 v166, v166
	s_nop 0
	v_mul_f32_e32 v160, 0xbfb8aa3b, v166
	v_mul_f32_e32 v162, v166, v166
	v_pk_mul_f32 v[168:169], v[124:125], v[160:161] op_sel_hi:[1,0]
	v_pk_mul_f32 v[170:171], v[126:127], v[160:161] op_sel_hi:[1,0]
	v_pk_mul_f32 v[172:173], v[120:121], v[160:161] op_sel_hi:[1,0]
	v_pk_mul_f32 v[174:175], v[122:123], v[160:161] op_sel_hi:[1,0]
	v_exp_f32_e32 v168, v168
	v_exp_f32_e32 v169, v169
	v_exp_f32_e32 v170, v170
	v_exp_f32_e32 v171, v171
	v_exp_f32_e32 v172, v172
	v_exp_f32_e32 v173, v173
	v_exp_f32_e32 v174, v174
	v_exp_f32_e32 v175, v175
	v_pk_add_f32 v[168:169], v[168:169], v[164:165]
	v_pk_add_f32 v[170:171], v[170:171], v[164:165]
	v_pk_add_f32 v[172:173], v[172:173], v[164:165]
	v_pk_add_f32 v[174:175], v[174:175], v[164:165]
	v_rcp_f32_e32 v168, v168
	v_rcp_f32_e32 v169, v169
	v_rcp_f32_e32 v170, v170
	v_rcp_f32_e32 v171, v171
	v_rcp_f32_e32 v172, v172
	v_rcp_f32_e32 v173, v173
	v_rcp_f32_e32 v174, v174
	v_rcp_f32_e32 v175, v175
	v_pk_mul_f32 v[124:125], v[124:125], v[116:117]
	v_pk_mul_f32 v[126:127], v[126:127], v[118:119]
	v_pk_mul_f32 v[120:121], v[120:121], v[112:113]
	v_pk_mul_f32 v[122:123], v[122:123], v[114:115]
	v_pk_mul_f32 v[124:125], v[124:125], v[168:169]
	v_pk_mul_f32 v[126:127], v[126:127], v[170:171]
	v_pk_mul_f32 v[120:121], v[120:121], v[172:173]
	v_pk_mul_f32 v[122:123], v[122:123], v[174:175]
	v_pk_mul_f32 v[124:125], v[124:125], v[162:163] op_sel_hi:[1,0]
	v_pk_mul_f32 v[126:127], v[126:127], v[162:163] op_sel_hi:[1,0]
	v_pk_mul_f32 v[120:121], v[120:121], v[162:163] op_sel_hi:[1,0]
	v_pk_mul_f32 v[122:123], v[122:123], v[162:163] op_sel_hi:[1,0]
	v_cvt_pk_bf16_f32 v116, v124, v125
	v_cvt_pk_bf16_f32 v117, v126, v127
	v_cvt_pk_bf16_f32 v118, v120, v121
	v_cvt_pk_bf16_f32 v119, v122, v123
	global_store_dwordx4 v[146:147], v[116:119], off
	s_waitcnt vmcnt(7)
	v_cvt_f32_u32_e32 v166, v179
	v_cvt_f32_u32_e32 v167, v178
	v_fmamk_f32 v166, v166, 0x4f800000, v167
	v_fmamk_f32 v166, v166, 0x2a800000, v159
	v_rsq_f32_e32 v166, v166
	s_nop 0
	v_mul_f32_e32 v160, 0xbfb8aa3b, v166
	v_mul_f32_e32 v162, v166, v166
	v_pk_mul_f32 v[168:169], v[108:109], v[160:161] op_sel_hi:[1,0]
	v_pk_mul_f32 v[170:171], v[110:111], v[160:161] op_sel_hi:[1,0]
	v_pk_mul_f32 v[172:173], v[104:105], v[160:161] op_sel_hi:[1,0]
	v_pk_mul_f32 v[174:175], v[106:107], v[160:161] op_sel_hi:[1,0]
	v_exp_f32_e32 v168, v168
	v_exp_f32_e32 v169, v169
	v_exp_f32_e32 v170, v170
	v_exp_f32_e32 v171, v171
	v_exp_f32_e32 v172, v172
	v_exp_f32_e32 v173, v173
	v_exp_f32_e32 v174, v174
	v_exp_f32_e32 v175, v175
	v_pk_add_f32 v[168:169], v[168:169], v[164:165]
	v_pk_add_f32 v[170:171], v[170:171], v[164:165]
	v_pk_add_f32 v[172:173], v[172:173], v[164:165]
	v_pk_add_f32 v[174:175], v[174:175], v[164:165]
	v_rcp_f32_e32 v168, v168
	v_rcp_f32_e32 v169, v169
	v_rcp_f32_e32 v170, v170
	v_rcp_f32_e32 v171, v171
	v_rcp_f32_e32 v172, v172
	v_rcp_f32_e32 v173, v173
	v_rcp_f32_e32 v174, v174
	v_rcp_f32_e32 v175, v175
	v_pk_mul_f32 v[108:109], v[108:109], v[100:101]
	v_pk_mul_f32 v[110:111], v[110:111], v[102:103]
	v_pk_mul_f32 v[104:105], v[104:105], v[96:97]
	v_pk_mul_f32 v[106:107], v[106:107], v[98:99]
	v_pk_mul_f32 v[108:109], v[108:109], v[168:169]
	v_pk_mul_f32 v[110:111], v[110:111], v[170:171]
	v_pk_mul_f32 v[104:105], v[104:105], v[172:173]
	v_pk_mul_f32 v[106:107], v[106:107], v[174:175]
	v_pk_mul_f32 v[108:109], v[108:109], v[162:163] op_sel_hi:[1,0]
	v_pk_mul_f32 v[110:111], v[110:111], v[162:163] op_sel_hi:[1,0]
	v_pk_mul_f32 v[104:105], v[104:105], v[162:163] op_sel_hi:[1,0]
	v_pk_mul_f32 v[106:107], v[106:107], v[162:163] op_sel_hi:[1,0]
	v_cvt_pk_bf16_f32 v100, v108, v109
	v_cvt_pk_bf16_f32 v101, v110, v111
	v_cvt_pk_bf16_f32 v102, v104, v105
	v_cvt_pk_bf16_f32 v103, v106, v107
	s_mov_b32 s100, 0x16000
	v_lshl_add_u64 v[148:149], v[146:147], 0, s[100:101]
	global_store_dwordx4 v[148:149], v[100:103], off
	s_waitcnt vmcnt(7)
; __device__ __forceinline__ float ss_scale(const u64* ss, int row) { return __builtin_amdgcn_rsqf((float)ss[row] * (1.f / 4294967296.f / 1024.f) + EPS); }
; __device__ __forceinline__ unsigned pkbf(float lo, float hi) { typedef __bf16 bf2_t __attribute__((ext_vector_type(2))); f32x2 v = {lo, hi}; bf2_t b = __builtin_convertvector(v, bf2_t); return __builtin_bit_cast(unsigned, b); }
; __device__ __forceinline__ float silu_f(float g) { return g * __builtin_amdgcn_rcpf(1.f + __builtin_amdgcn_exp2f(-g * LOG2E)); }
;     __device__ __forceinline__ void operator()(const f32x4 (&acc)[2][2][4][2], const pg8::Unit& u, int wr, int wc, int fr, int fq) const {
;         const int row0 = u.pm * 256 + wr * 64 + fr, col0 = u.pn * 128 + wc * 32 + 8 * fq;
; #pragma unroll
;         for (int ai = 0; ai < 2; ++ai)
; #pragma unroll
;             for (int m = 0; m < 4; ++m) {
;                 const int row = row0 + ai * 128 + m * 16;
;                 float s = ss_scale(ss, row);
;                 if constexpr (NN) s *= __builtin_amdgcn_rsqf(s * s * (float)ssw[row] * (1.f / 4294967296.f / 1024.f) + EPS);
;                 float a[8];
; #pragma unroll
;                 for (int n = 0; n < 2; ++n)
; #pragma unroll
;                     for (int i = 0; i < 4; ++i) { const float g = acc[ai][0][m][n][i] * s, uu = acc[ai][1][m][n][i] * s; a[4 * n + i] = silu_f(g) * uu; }
;                 u32x4 w; w.x = pkbf(a[0], a[1]); w.y = pkbf(a[2], a[3]); w.z = pkbf(a[4], a[5]); w.w = pkbf(a[6], a[7]);
;                 *(u32x4*)(O + (size_t)row * FF + col0) = w;
	v_cvt_f32_u32_e32 v166, v181
	v_cvt_f32_u32_e32 v167, v180
	v_fmamk_f32 v166, v166, 0x4f800000, v167
	v_fmamk_f32 v166, v166, 0x2a800000, v159
	v_rsq_f32_e32 v166, v166
	s_nop 0
	v_mul_f32_e32 v160, 0xbfb8aa3b, v166
	v_mul_f32_e32 v162, v166, v166
	v_pk_mul_f32 v[168:169], v[92:93], v[160:161] op_sel_hi:[1,0]
	v_pk_mul_f32 v[170:171], v[94:95], v[160:161] op_sel_hi:[1,0]
	v_pk_mul_f32 v[172:173], v[88:89], v[160:161] op_sel_hi:[1,0]
	v_pk_mul_f32 v[174:175], v[90:91], v[160:161] op_sel_hi:[1,0]
	v_exp_f32_e32 v168, v168
	v_exp_f32_e32 v169, v169
	v_exp_f32_e32 v170, v170
	v_exp_f32_e32 v171, v171
	v_exp_f32_e32 v172, v172
	v_exp_f32_e32 v173, v173
	v_exp_f32_e32 v174, v174
	v_exp_f32_e32 v175, v175
	v_pk_add_f32 v[168:169], v[168:169], v[164:165]
	v_pk_add_f32 v[170:171], v[170:171], v[164:165]
	v_pk_add_f32 v[172:173], v[172:173], v[164:165]
	v_pk_add_f32 v[174:175], v[174:175], v[164:165]
	v_rcp_f32_e32 v168, v168
	v_rcp_f32_e32 v169, v169
	v_rcp_f32_e32 v170, v170
	v_rcp_f32_e32 v171, v171
	v_rcp_f32_e32 v172, v172
	v_rcp_f32_e32 v173, v173
	v_rcp_f32_e32 v174, v174
	v_rcp_f32_e32 v175, v175
	v_pk_mul_f32 v[92:93], v[92:93], v[84:85]
	v_pk_mul_f32 v[94:95], v[94:95], v[86:87]
	v_pk_mul_f32 v[88:89], v[88:89], v[80:81]
	v_pk_mul_f32 v[90:91], v[90:91], v[82:83]
	v_pk_mul_f32 v[92:93], v[92:93], v[168:169]
	v_pk_mul_f32 v[94:95], v[94:95], v[170:171]
	v_pk_mul_f32 v[88:89], v[88:89], v[172:173]
	v_pk_mul_f32 v[90:91], v[90:91], v[174:175]
	v_pk_mul_f32 v[92:93], v[92:93], v[162:163] op_sel_hi:[1,0]
	v_pk_mul_f32 v[94:95], v[94:95], v[162:163] op_sel_hi:[1,0]
	v_pk_mul_f32 v[88:89], v[88:89], v[162:163] op_sel_hi:[1,0]
	v_pk_mul_f32 v[90:91], v[90:91], v[162:163] op_sel_hi:[1,0]
	v_cvt_pk_bf16_f32 v84, v92, v93
	v_cvt_pk_bf16_f32 v85, v94, v95
	v_cvt_pk_bf16_f32 v86, v88, v89
	v_cvt_pk_bf16_f32 v87, v90, v91
	s_mov_b32 s100, 0x2c000
	v_lshl_add_u64 v[148:149], v[146:147], 0, s[100:101]
	global_store_dwordx4 v[148:149], v[84:87], off
	s_waitcnt vmcnt(7)
	v_cvt_f32_u32_e32 v166, v183
	v_cvt_f32_u32_e32 v167, v182
	v_fmamk_f32 v166, v166, 0x4f800000, v167
	v_fmamk_f32 v166, v166, 0x2a800000, v159
	v_rsq_f32_e32 v166, v166
	s_nop 0
	v_mul_f32_e32 v160, 0xbfb8aa3b, v166
	v_mul_f32_e32 v162, v166, v166
	v_pk_mul_f32 v[168:169], v[76:77], v[160:161] op_sel_hi:[1,0]
	v_pk_mul_f32 v[170:171], v[78:79], v[160:161] op_sel_hi:[1,0]
	v_pk_mul_f32 v[172:173], v[72:73], v[160:161] op_sel_hi:[1,0]
	v_pk_mul_f32 v[174:175], v[74:75], v[160:161] op_sel_hi:[1,0]
	v_exp_f32_e32 v168, v168
	v_exp_f32_e32 v169, v169
	v_exp_f32_e32 v170, v170
	v_exp_f32_e32 v171, v171
	v_exp_f32_e32 v172, v172
	v_exp_f32_e32 v173, v173
	v_exp_f32_e32 v174, v174
	v_exp_f32_e32 v175, v175
	v_pk_add_f32 v[168:169], v[168:169], v[164:165]
	v_pk_add_f32 v[170:171], v[170:171], v[164:165]
	v_pk_add_f32 v[172:173], v[172:173], v[164:165]
	v_pk_add_f32 v[174:175], v[174:175], v[164:165]
	v_rcp_f32_e32 v168, v168
	v_rcp_f32_e32 v169, v169
	v_rcp_f32_e32 v170, v170
	v_rcp_f32_e32 v171, v171
	v_rcp_f32_e32 v172, v172
	v_rcp_f32_e32 v173, v173
	v_rcp_f32_e32 v174, v174
	v_rcp_f32_e32 v175, v175
	v_pk_mul_f32 v[76:77], v[76:77], v[68:69]
	v_pk_mul_f32 v[78:79], v[78:79], v[70:71]
	v_pk_mul_f32 v[72:73], v[72:73], v[64:65]
	v_pk_mul_f32 v[74:75], v[74:75], v[66:67]
	v_pk_mul_f32 v[76:77], v[76:77], v[168:169]
	v_pk_mul_f32 v[78:79], v[78:79], v[170:171]
	v_pk_mul_f32 v[72:73], v[72:73], v[172:173]
	v_pk_mul_f32 v[74:75], v[74:75], v[174:175]
	v_pk_mul_f32 v[76:77], v[76:77], v[162:163] op_sel_hi:[1,0]
	v_pk_mul_f32 v[78:79], v[78:79], v[162:163] op_sel_hi:[1,0]
	v_pk_mul_f32 v[72:73], v[72:73], v[162:163] op_sel_hi:[1,0]
	v_pk_mul_f32 v[74:75], v[74:75], v[162:163] op_sel_hi:[1,0]
	v_cvt_pk_bf16_f32 v68, v76, v77
	v_cvt_pk_bf16_f32 v69, v78, v79
	v_cvt_pk_bf16_f32 v70, v72, v73
	v_cvt_pk_bf16_f32 v71, v74, v75
	s_mov_b32 s100, 0x42000
	v_lshl_add_u64 v[148:149], v[146:147], 0, s[100:101]
	global_store_dwordx4 v[148:149], v[68:71], off
	s_waitcnt vmcnt(7)
	v_cvt_f32_u32_e32 v166, v185
	v_cvt_f32_u32_e32 v167, v184
	v_fmamk_f32 v166, v166, 0x4f800000, v167
	v_fmamk_f32 v166, v166, 0x2a800000, v159
	v_rsq_f32_e32 v166, v166
	s_nop 0
	v_mul_f32_e32 v160, 0xbfb8aa3b, v166
	v_mul_f32_e32 v162, v166, v166
	v_pk_mul_f32 v[168:169], v[60:61], v[160:161] op_sel_hi:[1,0]
	v_pk_mul_f32 v[170:171], v[62:63], v[160:161] op_sel_hi:[1,0]
	v_pk_mul_f32 v[172:173], v[56:57], v[160:161] op_sel_hi:[1,0]
	v_pk_mul_f32 v[174:175], v[58:59], v[160:161] op_sel_hi:[1,0]
	v_exp_f32_e32 v168, v168
	v_exp_f32_e32 v169, v169
	v_exp_f32_e32 v170, v170
	v_exp_f32_e32 v171, v171
	v_exp_f32_e32 v172, v172
	v_exp_f32_e32 v173, v173
	v_exp_f32_e32 v174, v174
	v_exp_f32_e32 v175, v175
	v_pk_add_f32 v[168:169], v[168:169], v[164:165]
	v_pk_add_f32 v[170:171], v[170:171], v[164:165]
	v_pk_add_f32 v[172:173], v[172:173], v[164:165]
	v_pk_add_f32 v[174:175], v[174:175], v[164:165]
	v_rcp_f32_e32 v168, v168
	v_rcp_f32_e32 v169, v169
	v_rcp_f32_e32 v170, v170
	v_rcp_f32_e32 v171, v171
	v_rcp_f32_e32 v172, v172
	v_rcp_f32_e32 v173, v173
	v_rcp_f32_e32 v174, v174
	v_rcp_f32_e32 v175, v175
	v_pk_mul_f32 v[60:61], v[60:61], v[52:53]
	v_pk_mul_f32 v[62:63], v[62:63], v[54:55]
	v_pk_mul_f32 v[56:57], v[56:57], v[48:49]
	v_pk_mul_f32 v[58:59], v[58:59], v[50:51]
	v_pk_mul_f32 v[60:61], v[60:61], v[168:169]
	v_pk_mul_f32 v[62:63], v[62:63], v[170:171]
	v_pk_mul_f32 v[56:57], v[56:57], v[172:173]
	v_pk_mul_f32 v[58:59], v[58:59], v[174:175]
	v_pk_mul_f32 v[60:61], v[60:61], v[162:163] op_sel_hi:[1,0]
	v_pk_mul_f32 v[62:63], v[62:63], v[162:163] op_sel_hi:[1,0]
	v_pk_mul_f32 v[56:57], v[56:57], v[162:163] op_sel_hi:[1,0]
	v_pk_mul_f32 v[58:59], v[58:59], v[162:163] op_sel_hi:[1,0]
	v_cvt_pk_bf16_f32 v52, v60, v61
	v_cvt_pk_bf16_f32 v53, v62, v63
	v_cvt_pk_bf16_f32 v54, v56, v57
	v_cvt_pk_bf16_f32 v55, v58, v59
	s_mov_b32 s100, 0xb0000
	v_lshl_add_u64 v[148:149], v[146:147], 0, s[100:101]
	global_store_dwordx4 v[148:149], v[52:55], off
	s_waitcnt vmcnt(7)
; __device__ __forceinline__ float ss_scale(const u64* ss, int row) { return __builtin_amdgcn_rsqf((float)ss[row] * (1.f / 4294967296.f / 1024.f) + EPS); }
; __device__ __forceinline__ unsigned pkbf(float lo, float hi) { typedef __bf16 bf2_t __attribute__((ext_vector_type(2))); f32x2 v = {lo, hi}; bf2_t b = __builtin_convertvector(v, bf2_t); return __builtin_bit_cast(unsigned, b); }
; __device__ __forceinline__ float silu_f(float g) { return g * __builtin_amdgcn_rcpf(1.f + __builtin_amdgcn_exp2f(-g * LOG2E)); }
;     __device__ __forceinline__ void operator()(const f32x4 (&acc)[2][2][4][2], const pg8::Unit& u, int wr, int wc, int fr, int fq) const {
;         const int row0 = u.pm * 256 + wr * 64 + fr, col0 = u.pn * 128 + wc * 32 + 8 * fq;
; #pragma unroll
;         for (int ai = 0; ai < 2; ++ai)
; #pragma unroll
;             for (int m = 0; m < 4; ++m) {
;                 const int row = row0 + ai * 128 + m * 16;
;                 float s = ss_scale(ss, row);
;                 if constexpr (NN) s *= __builtin_amdgcn_rsqf(s * s * (float)ssw[row] * (1.f / 4294967296.f / 1024.f) + EPS);
;                 float a[8];
; #pragma unroll
;                 for (int n = 0; n < 2; ++n)
; #pragma unroll
;                     for (int i = 0; i < 4; ++i) { const float g = acc[ai][0][m][n][i] * s, uu = acc[ai][1][m][n][i] * s; a[4 * n + i] = silu_f(g) * uu; }
;                 u32x4 w; w.x = pkbf(a[0], a[1]); w.y = pkbf(a[2], a[3]); w.z = pkbf(a[4], a[5]); w.w = pkbf(a[6], a[7]);
;                 *(u32x4*)(O + (size_t)row * FF + col0) = w;
	v_cvt_f32_u32_e32 v166, v187
	v_cvt_f32_u32_e32 v167, v186
	v_fmamk_f32 v166, v166, 0x4f800000, v167
	v_fmamk_f32 v166, v166, 0x2a800000, v159
	v_rsq_f32_e32 v166, v166
	s_nop 0
	v_mul_f32_e32 v160, 0xbfb8aa3b, v166
	v_mul_f32_e32 v162, v166, v166
	v_pk_mul_f32 v[168:169], v[44:45], v[160:161] op_sel_hi:[1,0]
	v_pk_mul_f32 v[170:171], v[46:47], v[160:161] op_sel_hi:[1,0]
	v_pk_mul_f32 v[172:173], v[40:41], v[160:161] op_sel_hi:[1,0]
	v_pk_mul_f32 v[174:175], v[42:43], v[160:161] op_sel_hi:[1,0]
	v_exp_f32_e32 v168, v168
	v_exp_f32_e32 v169, v169
	v_exp_f32_e32 v170, v170
	v_exp_f32_e32 v171, v171
	v_exp_f32_e32 v172, v172
	v_exp_f32_e32 v173, v173
	v_exp_f32_e32 v174, v174
	v_exp_f32_e32 v175, v175
	v_pk_add_f32 v[168:169], v[168:169], v[164:165]
	v_pk_add_f32 v[170:171], v[170:171], v[164:165]
	v_pk_add_f32 v[172:173], v[172:173], v[164:165]
	v_pk_add_f32 v[174:175], v[174:175], v[164:165]
	v_rcp_f32_e32 v168, v168
	v_rcp_f32_e32 v169, v169
	v_rcp_f32_e32 v170, v170
	v_rcp_f32_e32 v171, v171
	v_rcp_f32_e32 v172, v172
	v_rcp_f32_e32 v173, v173
	v_rcp_f32_e32 v174, v174
	v_rcp_f32_e32 v175, v175
	v_pk_mul_f32 v[44:45], v[44:45], v[36:37]
	v_pk_mul_f32 v[46:47], v[46:47], v[38:39]
	v_pk_mul_f32 v[40:41], v[40:41], v[32:33]
	v_pk_mul_f32 v[42:43], v[42:43], v[34:35]
	v_pk_mul_f32 v[44:45], v[44:45], v[168:169]
	v_pk_mul_f32 v[46:47], v[46:47], v[170:171]
	v_pk_mul_f32 v[40:41], v[40:41], v[172:173]
	v_pk_mul_f32 v[42:43], v[42:43], v[174:175]
	v_pk_mul_f32 v[44:45], v[44:45], v[162:163] op_sel_hi:[1,0]
	v_pk_mul_f32 v[46:47], v[46:47], v[162:163] op_sel_hi:[1,0]
	v_pk_mul_f32 v[40:41], v[40:41], v[162:163] op_sel_hi:[1,0]
	v_pk_mul_f32 v[42:43], v[42:43], v[162:163] op_sel_hi:[1,0]
	v_cvt_pk_bf16_f32 v36, v44, v45
	v_cvt_pk_bf16_f32 v37, v46, v47
	v_cvt_pk_bf16_f32 v38, v40, v41
	v_cvt_pk_bf16_f32 v39, v42, v43
	s_mov_b32 s100, 0xc6000
	v_lshl_add_u64 v[148:149], v[146:147], 0, s[100:101]
	global_store_dwordx4 v[148:149], v[36:39], off
	s_waitcnt vmcnt(7)
	v_cvt_f32_u32_e32 v166, v189
	v_cvt_f32_u32_e32 v167, v188
	v_fmamk_f32 v166, v166, 0x4f800000, v167
	v_fmamk_f32 v166, v166, 0x2a800000, v159
	v_rsq_f32_e32 v166, v166
	s_nop 0
	v_mul_f32_e32 v160, 0xbfb8aa3b, v166
	v_mul_f32_e32 v162, v166, v166
	v_pk_mul_f32 v[168:169], v[28:29], v[160:161] op_sel_hi:[1,0]
	v_pk_mul_f32 v[170:171], v[30:31], v[160:161] op_sel_hi:[1,0]
	v_pk_mul_f32 v[172:173], v[24:25], v[160:161] op_sel_hi:[1,0]
	v_pk_mul_f32 v[174:175], v[26:27], v[160:161] op_sel_hi:[1,0]
	v_exp_f32_e32 v168, v168
	v_exp_f32_e32 v169, v169
	v_exp_f32_e32 v170, v170
	v_exp_f32_e32 v171, v171
	v_exp_f32_e32 v172, v172
	v_exp_f32_e32 v173, v173
	v_exp_f32_e32 v174, v174
	v_exp_f32_e32 v175, v175
	v_pk_add_f32 v[168:169], v[168:169], v[164:165]
	v_pk_add_f32 v[170:171], v[170:171], v[164:165]
	v_pk_add_f32 v[172:173], v[172:173], v[164:165]
	v_pk_add_f32 v[174:175], v[174:175], v[164:165]
	v_rcp_f32_e32 v168, v168
	v_rcp_f32_e32 v169, v169
	v_rcp_f32_e32 v170, v170
	v_rcp_f32_e32 v171, v171
	v_rcp_f32_e32 v172, v172
	v_rcp_f32_e32 v173, v173
	v_rcp_f32_e32 v174, v174
	v_rcp_f32_e32 v175, v175
	v_pk_mul_f32 v[28:29], v[28:29], v[20:21]
	v_pk_mul_f32 v[30:31], v[30:31], v[22:23]
	v_pk_mul_f32 v[24:25], v[24:25], v[16:17]
	v_pk_mul_f32 v[26:27], v[26:27], v[18:19]
	v_pk_mul_f32 v[28:29], v[28:29], v[168:169]
	v_pk_mul_f32 v[30:31], v[30:31], v[170:171]
	v_pk_mul_f32 v[24:25], v[24:25], v[172:173]
	v_pk_mul_f32 v[26:27], v[26:27], v[174:175]
	v_pk_mul_f32 v[28:29], v[28:29], v[162:163] op_sel_hi:[1,0]
	v_pk_mul_f32 v[30:31], v[30:31], v[162:163] op_sel_hi:[1,0]
	v_pk_mul_f32 v[24:25], v[24:25], v[162:163] op_sel_hi:[1,0]
	v_pk_mul_f32 v[26:27], v[26:27], v[162:163] op_sel_hi:[1,0]
	v_cvt_pk_bf16_f32 v20, v28, v29
	v_cvt_pk_bf16_f32 v21, v30, v31
	v_cvt_pk_bf16_f32 v22, v24, v25
	v_cvt_pk_bf16_f32 v23, v26, v27
	s_mov_b32 s100, 0xdc000
	v_lshl_add_u64 v[148:149], v[146:147], 0, s[100:101]
	global_store_dwordx4 v[148:149], v[20:23], off
	s_waitcnt vmcnt(7)
	v_cvt_f32_u32_e32 v166, v191
	v_cvt_f32_u32_e32 v167, v190
	v_fmamk_f32 v166, v166, 0x4f800000, v167
	v_fmamk_f32 v166, v166, 0x2a800000, v159
	v_rsq_f32_e32 v166, v166
	s_nop 0
	v_mul_f32_e32 v160, 0xbfb8aa3b, v166
	v_mul_f32_e32 v162, v166, v166
	v_pk_mul_f32 v[168:169], v[12:13], v[160:161] op_sel_hi:[1,0]
	v_pk_mul_f32 v[170:171], v[14:15], v[160:161] op_sel_hi:[1,0]
	v_pk_mul_f32 v[172:173], v[8:9], v[160:161] op_sel_hi:[1,0]
	v_pk_mul_f32 v[174:175], v[10:11], v[160:161] op_sel_hi:[1,0]
	v_exp_f32_e32 v168, v168
	v_exp_f32_e32 v169, v169
	v_exp_f32_e32 v170, v170
	v_exp_f32_e32 v171, v171
	v_exp_f32_e32 v172, v172
	v_exp_f32_e32 v173, v173
	v_exp_f32_e32 v174, v174
	v_exp_f32_e32 v175, v175
	v_pk_add_f32 v[168:169], v[168:169], v[164:165]
	v_pk_add_f32 v[170:171], v[170:171], v[164:165]
	v_pk_add_f32 v[172:173], v[172:173], v[164:165]
	v_pk_add_f32 v[174:175], v[174:175], v[164:165]
	v_rcp_f32_e32 v168, v168
	v_rcp_f32_e32 v169, v169
	v_rcp_f32_e32 v170, v170
	v_rcp_f32_e32 v171, v171
	v_rcp_f32_e32 v172, v172
	v_rcp_f32_e32 v173, v173
	v_rcp_f32_e32 v174, v174
	v_rcp_f32_e32 v175, v175
	v_pk_mul_f32 v[12:13], v[12:13], v[4:5]
	v_pk_mul_f32 v[14:15], v[14:15], v[6:7]
	v_pk_mul_f32 v[8:9], v[8:9], v[0:1]
	v_pk_mul_f32 v[10:11], v[10:11], v[2:3]
	v_pk_mul_f32 v[12:13], v[12:13], v[168:169]
	v_pk_mul_f32 v[14:15], v[14:15], v[170:171]
	v_pk_mul_f32 v[8:9], v[8:9], v[172:173]
	v_pk_mul_f32 v[10:11], v[10:11], v[174:175]
	v_pk_mul_f32 v[12:13], v[12:13], v[162:163] op_sel_hi:[1,0]
	v_pk_mul_f32 v[14:15], v[14:15], v[162:163] op_sel_hi:[1,0]
	v_pk_mul_f32 v[8:9], v[8:9], v[162:163] op_sel_hi:[1,0]
	v_pk_mul_f32 v[10:11], v[10:11], v[162:163] op_sel_hi:[1,0]
	v_cvt_pk_bf16_f32 v4, v12, v13
	v_cvt_pk_bf16_f32 v5, v14, v15
	v_cvt_pk_bf16_f32 v6, v8, v9
	v_cvt_pk_bf16_f32 v7, v10, v11
	s_mov_b32 s100, 0xf2000
	v_lshl_add_u64 v[148:149], v[146:147], 0, s[100:101]
	global_store_dwordx4 v[148:149], v[4:7], off
	s_cbranch_vccnz .LBB0_275
	s_andn2_b64 vcc, exec, s[4:5]
	s_cbranch_vccnz .LBB0_274
	s_barrier
	s_branch .LBB0_274

; __device__ __forceinline__ float ss_scale(const u64* ss, int row) { return __builtin_amdgcn_rsqf((float)ss[row] * (1.f / 4294967296.f / 1024.f) + EPS); }
; __device__ __forceinline__ unsigned pkbf(float lo, float hi) { typedef __bf16 bf2_t __attribute__((ext_vector_type(2))); f32x2 v = {lo, hi}; bf2_t b = __builtin_convertvector(v, bf2_t); return __builtin_bit_cast(unsigned, b); }
; __device__ __forceinline__ float silu_f(float g) { return g * __builtin_amdgcn_rcpf(1.f + __builtin_amdgcn_exp2f(-g * LOG2E)); }
;     __device__ __forceinline__ void operator()(const f32x4 (&acc)[2][2][4][2], const pg8::Unit& u, int wr, int wc, int fr, int fq) const {
;         const int row0 = u.pm * 256 + wr * 64 + fr, col0 = u.pn * 128 + wc * 32 + 8 * fq;
; #pragma unroll
;         for (int ai = 0; ai < 2; ++ai)
; #pragma unroll
;             for (int m = 0; m < 4; ++m) {
;                 const int row = row0 + ai * 128 + m * 16;
;                 float s = ss_scale(ss, row);
;                 if constexpr (NN) s *= __builtin_amdgcn_rsqf(s * s * (float)ssw[row] * (1.f / 4294967296.f / 1024.f) + EPS);
;                 float a[8];
; #pragma unroll
;                 for (int n = 0; n < 2; ++n)
; #pragma unroll
;                     for (int i = 0; i < 4; ++i) { const float g = acc[ai][0][m][n][i] * s, uu = acc[ai][1][m][n][i] * s; a[4 * n + i] = silu_f(g) * uu; }
;                 u32x4 w; w.x = pkbf(a[0], a[1]); w.y = pkbf(a[2], a[3]); w.z = pkbf(a[4], a[5]); w.w = pkbf(a[6], a[7]);
;                 *(u32x4*)(O + (size_t)row * FF + col0) = w;
.LBB0_852:
	v_lshl_add_u32 v144, s22, 8, v152
	v_mov_b32_e32 v145, 0
	v_lshl_add_u64 v[150:151], v[144:145], 3, s[8:9]
	global_load_dwordx2 v[176:177], v[150:151], off
	global_load_dwordx2 v[178:179], v[150:151], off offset:128
	global_load_dwordx2 v[180:181], v[150:151], off offset:256
	global_load_dwordx2 v[182:183], v[150:151], off offset:384
	global_load_dwordx2 v[184:185], v[150:151], off offset:1024
	global_load_dwordx2 v[186:187], v[150:151], off offset:1152
	global_load_dwordx2 v[188:189], v[150:151], off offset:1280
	global_load_dwordx2 v[190:191], v[150:151], off offset:1408
	v_lshl_or_b32 v148, s53, 7, v153
	v_mul_u32_u24_e32 v146, s52, v144
	v_lshl_add_u32 v146, v148, 1, v146
	v_mov_b32_e32 v147, 0
	v_lshl_add_u64 v[146:147], v[146:147], 0, s[6:7]
	v_mov_b32_e32 v164, 1.0
	v_mov_b32_e32 v165, 1.0
	s_andn2_b64 vcc, exec, s[2:3]
	s_mov_b64 s[2:3], -1
	s_mov_b32 s101, 0
	s_waitcnt vmcnt(7)
	v_cvt_f32_u32_e32 v166, v177
	v_cvt_f32_u32_e32 v167, v176
	v_fmamk_f32 v166, v166, 0x4f800000, v167
	v_fmamk_f32 v166, v166, 0x2a800000, v159
	v_rsq_f32_e32 v166, v166
	s_nop 0
	v_mul_f32_e32 v160, 0xbfb8aa3b, v166
	v_mul_f32_e32 v162, v166, v166
	v_pk_mul_f32 v[168:169], v[124:125], v[160:161] op_sel_hi:[1,0]
	v_pk_mul_f32 v[170:171], v[126:127], v[160:161] op_sel_hi:[1,0]
	v_pk_mul_f32 v[172:173], v[120:121], v[160:161] op_sel_hi:[1,0]
	v_pk_mul_f32 v[174:175], v[122:123], v[160:161] op_sel_hi:[1,0]
	v_exp_f32_e32 v168, v168
	v_exp_f32_e32 v169, v169
	v_exp_f32_e32 v170, v170
	v_exp_f32_e32 v171, v171
	v_exp_f32_e32 v172, v172
	v_exp_f32_e32 v173, v173
	v_exp_f32_e32 v174, v174
	v_exp_f32_e32 v175, v175
	v_pk_add_f32 v[168:169], v[168:169], v[164:165]
	v_pk_add_f32 v[170:171], v[170:171], v[164:165]
	v_pk_add_f32 v[172:173], v[172:173], v[164:165]
	v_pk_add_f32 v[174:175], v[174:175], v[164:165]
	v_rcp_f32_e32 v168, v168
	v_rcp_f32_e32 v169, v169
	v_rcp_f32_e32 v170, v170
	v_rcp_f32_e32 v171, v171
	v_rcp_f32_e32 v172, v172
	v_rcp_f32_e32 v173, v173
	v_rcp_f32_e32 v174, v174
	v_rcp_f32_e32 v175, v175
	v_pk_mul_f32 v[124:125], v[124:125], v[116:117]
	v_pk_mul_f32 v[126:127], v[126:127], v[118:119]
	v_pk_mul_f32 v[120:121], v[120:121], v[112:113]
	v_pk_mul_f32 v[122:123], v[122:123], v[114:115]
	v_pk_mul_f32 v[124:125], v[124:125], v[168:169]
	v_pk_mul_f32 v[126:127], v[126:127], v[170:171]
	v_pk_mul_f32 v[120:121], v[120:121], v[172:173]
	v_pk_mul_f32 v[122:123], v[122:123], v[174:175]
	v_pk_mul_f32 v[124:125], v[124:125], v[162:163] op_sel_hi:[1,0]
	v_pk_mul_f32 v[126:127], v[126:127], v[162:163] op_sel_hi:[1,0]
	v_pk_mul_f32 v[120:121], v[120:121], v[162:163] op_sel_hi:[1,0]
	v_pk_mul_f32 v[122:123], v[122:123], v[162:163] op_sel_hi:[1,0]
	v_cvt_pk_bf16_f32 v116, v124, v125
	v_cvt_pk_bf16_f32 v117, v126, v127
	v_cvt_pk_bf16_f32 v118, v120, v121
	v_cvt_pk_bf16_f32 v119, v122, v123
	global_store_dwordx4 v[146:147], v[116:119], off
	s_waitcnt vmcnt(7)
	v_cvt_f32_u32_e32 v166, v179
	v_cvt_f32_u32_e32 v167, v178
	v_fmamk_f32 v166, v166, 0x4f800000, v167
	v_fmamk_f32 v166, v166, 0x2a800000, v159
	v_rsq_f32_e32 v166, v166
	s_nop 0
	v_mul_f32_e32 v160, 0xbfb8aa3b, v166
	v_mul_f32_e32 v162, v166, v166
	v_pk_mul_f32 v[168:169], v[108:109], v[160:161] op_sel_hi:[1,0]
	v_pk_mul_f32 v[170:171], v[110:111], v[160:161] op_sel_hi:[1,0]
	v_pk_mul_f32 v[172:173], v[104:105], v[160:161] op_sel_hi:[1,0]
	v_pk_mul_f32 v[174:175], v[106:107], v[160:161] op_sel_hi:[1,0]
	v_exp_f32_e32 v168, v168
	v_exp_f32_e32 v169, v169
	v_exp_f32_e32 v170, v170
	v_exp_f32_e32 v171, v171
	v_exp_f32_e32 v172, v172
	v_exp_f32_e32 v173, v173
	v_exp_f32_e32 v174, v174
	v_exp_f32_e32 v175, v175
	v_pk_add_f32 v[168:169], v[168:169], v[164:165]
	v_pk_add_f32 v[170:171], v[170:171], v[164:165]
	v_pk_add_f32 v[172:173], v[172:173], v[164:165]
	v_pk_add_f32 v[174:175], v[174:175], v[164:165]
	v_rcp_f32_e32 v168, v168
	v_rcp_f32_e32 v169, v169
	v_rcp_f32_e32 v170, v170
	v_rcp_f32_e32 v171, v171
	v_rcp_f32_e32 v172, v172
	v_rcp_f32_e32 v173, v173
	v_rcp_f32_e32 v174, v174
	v_rcp_f32_e32 v175, v175
	v_pk_mul_f32 v[108:109], v[108:109], v[100:101]
	v_pk_mul_f32 v[110:111], v[110:111], v[102:103]
	v_pk_mul_f32 v[104:105], v[104:105], v[96:97]
	v_pk_mul_f32 v[106:107], v[106:107], v[98:99]
	v_pk_mul_f32 v[108:109], v[108:109], v[168:169]
	v_pk_mul_f32 v[110:111], v[110:111], v[170:171]
	v_pk_mul_f32 v[104:105], v[104:105], v[172:173]
	v_pk_mul_f32 v[106:107], v[106:107], v[174:175]
	v_pk_mul_f32 v[108:109], v[108:109], v[162:163] op_sel_hi:[1,0]
	v_pk_mul_f32 v[110:111], v[110:111], v[162:163] op_sel_hi:[1,0]
	v_pk_mul_f32 v[104:105], v[104:105], v[162:163] op_sel_hi:[1,0]
	v_pk_mul_f32 v[106:107], v[106:107], v[162:163] op_sel_hi:[1,0]
	v_cvt_pk_bf16_f32 v100, v108, v109
	v_cvt_pk_bf16_f32 v101, v110, v111
	v_cvt_pk_bf16_f32 v102, v104, v105
	v_cvt_pk_bf16_f32 v103, v106, v107
	s_mov_b32 s100, 0x16000
	v_lshl_add_u64 v[148:149], v[146:147], 0, s[100:101]
	global_store_dwordx4 v[148:149], v[100:103], off
	s_waitcnt vmcnt(7)
; __device__ __forceinline__ float ss_scale(const u64* ss, int row) { return __builtin_amdgcn_rsqf((float)ss[row] * (1.f / 4294967296.f / 1024.f) + EPS); }
; __device__ __forceinline__ unsigned pkbf(float lo, float hi) { typedef __bf16 bf2_t __attribute__((ext_vector_type(2))); f32x2 v = {lo, hi}; bf2_t b = __builtin_convertvector(v, bf2_t); return __builtin_bit_cast(unsigned, b); }
; __device__ __forceinline__ float silu_f(float g) { return g * __builtin_amdgcn_rcpf(1.f + __builtin_amdgcn_exp2f(-g * LOG2E)); }
;     __device__ __forceinline__ void operator()(const f32x4 (&acc)[2][2][4][2], const pg8::Unit& u, int wr, int wc, int fr, int fq) const {
;         const int row0 = u.pm * 256 + wr * 64 + fr, col0 = u.pn * 128 + wc * 32 + 8 * fq;
; #pragma unroll
;         for (int ai = 0; ai < 2; ++ai)
; #pragma unroll
;             for (int m = 0; m < 4; ++m) {
;                 const int row = row0 + ai * 128 + m * 16;
;                 float s = ss_scale(ss, row);
;                 if constexpr (NN) s *= __builtin_amdgcn_rsqf(s * s * (float)ssw[row] * (1.f / 4294967296.f / 1024.f) + EPS);
;                 float a[8];
; #pragma unroll
;                 for (int n = 0; n < 2; ++n)
; #pragma unroll
;                     for (int i = 0; i < 4; ++i) { const float g = acc[ai][0][m][n][i] * s, uu = acc[ai][1][m][n][i] * s; a[4 * n + i] = silu_f(g) * uu; }
;                 u32x4 w; w.x = pkbf(a[0], a[1]); w.y = pkbf(a[2], a[3]); w.z = pkbf(a[4], a[5]); w.w = pkbf(a[6], a[7]);
;                 *(u32x4*)(O + (size_t)row * FF + col0) = w;
	v_cvt_f32_u32_e32 v166, v181
	v_cvt_f32_u32_e32 v167, v180
	v_fmamk_f32 v166, v166, 0x4f800000, v167
	v_fmamk_f32 v166, v166, 0x2a800000, v159
	v_rsq_f32_e32 v166, v166
	s_nop 0
	v_mul_f32_e32 v160, 0xbfb8aa3b, v166
	v_mul_f32_e32 v162, v166, v166
	v_pk_mul_f32 v[168:169], v[92:93], v[160:161] op_sel_hi:[1,0]
	v_pk_mul_f32 v[170:171], v[94:95], v[160:161] op_sel_hi:[1,0]
	v_pk_mul_f32 v[172:173], v[88:89], v[160:161] op_sel_hi:[1,0]
	v_pk_mul_f32 v[174:175], v[90:91], v[160:161] op_sel_hi:[1,0]
	v_exp_f32_e32 v168, v168
	v_exp_f32_e32 v169, v169
	v_exp_f32_e32 v170, v170
	v_exp_f32_e32 v171, v171
	v_exp_f32_e32 v172, v172
	v_exp_f32_e32 v173, v173
	v_exp_f32_e32 v174, v174
	v_exp_f32_e32 v175, v175
	v_pk_add_f32 v[168:169], v[168:169], v[164:165]
	v_pk_add_f32 v[170:171], v[170:171], v[164:165]
	v_pk_add_f32 v[172:173], v[172:173], v[164:165]
	v_pk_add_f32 v[174:175], v[174:175], v[164:165]
	v_rcp_f32_e32 v168, v168
	v_rcp_f32_e32 v169, v169
	v_rcp_f32_e32 v170, v170
	v_rcp_f32_e32 v171, v171
	v_rcp_f32_e32 v172, v172
	v_rcp_f32_e32 v173, v173
	v_rcp_f32_e32 v174, v174
	v_rcp_f32_e32 v175, v175
	v_pk_mul_f32 v[92:93], v[92:93], v[84:85]
	v_pk_mul_f32 v[94:95], v[94:95], v[86:87]
	v_pk_mul_f32 v[88:89], v[88:89], v[80:81]
	v_pk_mul_f32 v[90:91], v[90:91], v[82:83]
	v_pk_mul_f32 v[92:93], v[92:93], v[168:169]
	v_pk_mul_f32 v[94:95], v[94:95], v[170:171]
	v_pk_mul_f32 v[88:89], v[88:89], v[172:173]
	v_pk_mul_f32 v[90:91], v[90:91], v[174:175]
	v_pk_mul_f32 v[92:93], v[92:93], v[162:163] op_sel_hi:[1,0]
	v_pk_mul_f32 v[94:95], v[94:95], v[162:163] op_sel_hi:[1,0]
	v_pk_mul_f32 v[88:89], v[88:89], v[162:163] op_sel_hi:[1,0]
	v_pk_mul_f32 v[90:91], v[90:91], v[162:163] op_sel_hi:[1,0]
	v_cvt_pk_bf16_f32 v84, v92, v93
	v_cvt_pk_bf16_f32 v85, v94, v95
	v_cvt_pk_bf16_f32 v86, v88, v89
	v_cvt_pk_bf16_f32 v87, v90, v91
	s_mov_b32 s100, 0x2c000
	v_lshl_add_u64 v[148:149], v[146:147], 0, s[100:101]
	global_store_dwordx4 v[148:149], v[84:87], off
	s_waitcnt vmcnt(7)
	v_cvt_f32_u32_e32 v166, v183
	v_cvt_f32_u32_e32 v167, v182
	v_fmamk_f32 v166, v166, 0x4f800000, v167
	v_fmamk_f32 v166, v166, 0x2a800000, v159
	v_rsq_f32_e32 v166, v166
	s_nop 0
	v_mul_f32_e32 v160, 0xbfb8aa3b, v166
	v_mul_f32_e32 v162, v166, v166
	v_pk_mul_f32 v[168:169], v[76:77], v[160:161] op_sel_hi:[1,0]
	v_pk_mul_f32 v[170:171], v[78:79], v[160:161] op_sel_hi:[1,0]
	v_pk_mul_f32 v[172:173], v[72:73], v[160:161] op_sel_hi:[1,0]
	v_pk_mul_f32 v[174:175], v[74:75], v[160:161] op_sel_hi:[1,0]
	v_exp_f32_e32 v168, v168
	v_exp_f32_e32 v169, v169
	v_exp_f32_e32 v170, v170
	v_exp_f32_e32 v171, v171
	v_exp_f32_e32 v172, v172
	v_exp_f32_e32 v173, v173
	v_exp_f32_e32 v174, v174
	v_exp_f32_e32 v175, v175
	v_pk_add_f32 v[168:169], v[168:169], v[164:165]
	v_pk_add_f32 v[170:171], v[170:171], v[164:165]
	v_pk_add_f32 v[172:173], v[172:173], v[164:165]
	v_pk_add_f32 v[174:175], v[174:175], v[164:165]
	v_rcp_f32_e32 v168, v168
	v_rcp_f32_e32 v169, v169
	v_rcp_f32_e32 v170, v170
	v_rcp_f32_e32 v171, v171
	v_rcp_f32_e32 v172, v172
	v_rcp_f32_e32 v173, v173
	v_rcp_f32_e32 v174, v174
	v_rcp_f32_e32 v175, v175
	v_pk_mul_f32 v[76:77], v[76:77], v[68:69]
	v_pk_mul_f32 v[78:79], v[78:79], v[70:71]
	v_pk_mul_f32 v[72:73], v[72:73], v[64:65]
	v_pk_mul_f32 v[74:75], v[74:75], v[66:67]
	v_pk_mul_f32 v[76:77], v[76:77], v[168:169]
	v_pk_mul_f32 v[78:79], v[78:79], v[170:171]
	v_pk_mul_f32 v[72:73], v[72:73], v[172:173]
	v_pk_mul_f32 v[74:75], v[74:75], v[174:175]
	v_pk_mul_f32 v[76:77], v[76:77], v[162:163] op_sel_hi:[1,0]
	v_pk_mul_f32 v[78:79], v[78:79], v[162:163] op_sel_hi:[1,0]
	v_pk_mul_f32 v[72:73], v[72:73], v[162:163] op_sel_hi:[1,0]
	v_pk_mul_f32 v[74:75], v[74:75], v[162:163] op_sel_hi:[1,0]
	v_cvt_pk_bf16_f32 v68, v76, v77
	v_cvt_pk_bf16_f32 v69, v78, v79
	v_cvt_pk_bf16_f32 v70, v72, v73
	v_cvt_pk_bf16_f32 v71, v74, v75
	s_mov_b32 s100, 0x42000
	v_lshl_add_u64 v[148:149], v[146:147], 0, s[100:101]
	global_store_dwordx4 v[148:149], v[68:71], off
	s_waitcnt vmcnt(7)
	v_cvt_f32_u32_e32 v166, v185
	v_cvt_f32_u32_e32 v167, v184
	v_fmamk_f32 v166, v166, 0x4f800000, v167
	v_fmamk_f32 v166, v166, 0x2a800000, v159
	v_rsq_f32_e32 v166, v166
	s_nop 0
	v_mul_f32_e32 v160, 0xbfb8aa3b, v166
	v_mul_f32_e32 v162, v166, v166
	v_pk_mul_f32 v[168:169], v[60:61], v[160:161] op_sel_hi:[1,0]
	v_pk_mul_f32 v[170:171], v[62:63], v[160:161] op_sel_hi:[1,0]
	v_pk_mul_f32 v[172:173], v[56:57], v[160:161] op_sel_hi:[1,0]
	v_pk_mul_f32 v[174:175], v[58:59], v[160:161] op_sel_hi:[1,0]
	v_exp_f32_e32 v168, v168
	v_exp_f32_e32 v169, v169
	v_exp_f32_e32 v170, v170
	v_exp_f32_e32 v171, v171
	v_exp_f32_e32 v172, v172
	v_exp_f32_e32 v173, v173
	v_exp_f32_e32 v174, v174
	v_exp_f32_e32 v175, v175
	v_pk_add_f32 v[168:169], v[168:169], v[164:165]
	v_pk_add_f32 v[170:171], v[170:171], v[164:165]
	v_pk_add_f32 v[172:173], v[172:173], v[164:165]
	v_pk_add_f32 v[174:175], v[174:175], v[164:165]
	v_rcp_f32_e32 v168, v168
	v_rcp_f32_e32 v169, v169
	v_rcp_f32_e32 v170, v170
	v_rcp_f32_e32 v171, v171
	v_rcp_f32_e32 v172, v172
	v_rcp_f32_e32 v173, v173
	v_rcp_f32_e32 v174, v174
	v_rcp_f32_e32 v175, v175
	v_pk_mul_f32 v[60:61], v[60:61], v[52:53]
	v_pk_mul_f32 v[62:63], v[62:63], v[54:55]
	v_pk_mul_f32 v[56:57], v[56:57], v[48:49]
	v_pk_mul_f32 v[58:59], v[58:59], v[50:51]
	v_pk_mul_f32 v[60:61], v[60:61], v[168:169]
	v_pk_mul_f32 v[62:63], v[62:63], v[170:171]
	v_pk_mul_f32 v[56:57], v[56:57], v[172:173]
	v_pk_mul_f32 v[58:59], v[58:59], v[174:175]
	v_pk_mul_f32 v[60:61], v[60:61], v[162:163] op_sel_hi:[1,0]
	v_pk_mul_f32 v[62:63], v[62:63], v[162:163] op_sel_hi:[1,0]
	v_pk_mul_f32 v[56:57], v[56:57], v[162:163] op_sel_hi:[1,0]
	v_pk_mul_f32 v[58:59], v[58:59], v[162:163] op_sel_hi:[1,0]
	v_cvt_pk_bf16_f32 v52, v60, v61
	v_cvt_pk_bf16_f32 v53, v62, v63
	v_cvt_pk_bf16_f32 v54, v56, v57
	v_cvt_pk_bf16_f32 v55, v58, v59
	s_mov_b32 s100, 0xb0000
	v_lshl_add_u64 v[148:149], v[146:147], 0, s[100:101]
	global_store_dwordx4 v[148:149], v[52:55], off
	s_waitcnt vmcnt(7)
; __device__ __forceinline__ float ss_scale(const u64* ss, int row) { return __builtin_amdgcn_rsqf((float)ss[row] * (1.f / 4294967296.f / 1024.f) + EPS); }
; __device__ __forceinline__ unsigned pkbf(float lo, float hi) { typedef __bf16 bf2_t __attribute__((ext_vector_type(2))); f32x2 v = {lo, hi}; bf2_t b = __builtin_convertvector(v, bf2_t); return __builtin_bit_cast(unsigned, b); }
; __device__ __forceinline__ float silu_f(float g) { return g * __builtin_amdgcn_rcpf(1.f + __builtin_amdgcn_exp2f(-g * LOG2E)); }
;     __device__ __forceinline__ void operator()(const f32x4 (&acc)[2][2][4][2], const pg8::Unit& u, int wr, int wc, int fr, int fq) const {
;         const int row0 = u.pm * 256 + wr * 64 + fr, col0 = u.pn * 128 + wc * 32 + 8 * fq;
; #pragma unroll
;         for (int ai = 0; ai < 2; ++ai)
; #pragma unroll
;             for (int m = 0; m < 4; ++m) {
;                 const int row = row0 + ai * 128 + m * 16;
;                 float s = ss_scale(ss, row);
;                 if constexpr (NN) s *= __builtin_amdgcn_rsqf(s * s * (float)ssw[row] * (1.f / 4294967296.f / 1024.f) + EPS);
;                 float a[8];
; #pragma unroll
;                 for (int n = 0; n < 2; ++n)
; #pragma unroll
;                     for (int i = 0; i < 4; ++i) { const float g = acc[ai][0][m][n][i] * s, uu = acc[ai][1][m][n][i] * s; a[4 * n + i] = silu_f(g) * uu; }
;                 u32x4 w; w.x = pkbf(a[0], a[1]); w.y = pkbf(a[2], a[3]); w.z = pkbf(a[4], a[5]); w.w = pkbf(a[6], a[7]);
;                 *(u32x4*)(O + (size_t)row * FF + col0) = w;
	v_cvt_f32_u32_e32 v166, v187
	v_cvt_f32_u32_e32 v167, v186
	v_fmamk_f32 v166, v166, 0x4f800000, v167
	v_fmamk_f32 v166, v166, 0x2a800000, v159
	v_rsq_f32_e32 v166, v166
	s_nop 0
	v_mul_f32_e32 v160, 0xbfb8aa3b, v166
	v_mul_f32_e32 v162, v166, v166
	v_pk_mul_f32 v[168:169], v[44:45], v[160:161] op_sel_hi:[1,0]
	v_pk_mul_f32 v[170:171], v[46:47], v[160:161] op_sel_hi:[1,0]
	v_pk_mul_f32 v[172:173], v[40:41], v[160:161] op_sel_hi:[1,0]
	v_pk_mul_f32 v[174:175], v[42:43], v[160:161] op_sel_hi:[1,0]
	v_exp_f32_e32 v168, v168
	v_exp_f32_e32 v169, v169
	v_exp_f32_e32 v170, v170
	v_exp_f32_e32 v171, v171
	v_exp_f32_e32 v172, v172
	v_exp_f32_e32 v173, v173
	v_exp_f32_e32 v174, v174
	v_exp_f32_e32 v175, v175
	v_pk_add_f32 v[168:169], v[168:169], v[164:165]
	v_pk_add_f32 v[170:171], v[170:171], v[164:165]
	v_pk_add_f32 v[172:173], v[172:173], v[164:165]
	v_pk_add_f32 v[174:175], v[174:175], v[164:165]
	v_rcp_f32_e32 v168, v168
	v_rcp_f32_e32 v169, v169
	v_rcp_f32_e32 v170, v170
	v_rcp_f32_e32 v171, v171
	v_rcp_f32_e32 v172, v172
	v_rcp_f32_e32 v173, v173
	v_rcp_f32_e32 v174, v174
	v_rcp_f32_e32 v175, v175
	v_pk_mul_f32 v[44:45], v[44:45], v[36:37]
	v_pk_mul_f32 v[46:47], v[46:47], v[38:39]
	v_pk_mul_f32 v[40:41], v[40:41], v[32:33]
	v_pk_mul_f32 v[42:43], v[42:43], v[34:35]
	v_pk_mul_f32 v[44:45], v[44:45], v[168:169]
	v_pk_mul_f32 v[46:47], v[46:47], v[170:171]
	v_pk_mul_f32 v[40:41], v[40:41], v[172:173]
	v_pk_mul_f32 v[42:43], v[42:43], v[174:175]
	v_pk_mul_f32 v[44:45], v[44:45], v[162:163] op_sel_hi:[1,0]
	v_pk_mul_f32 v[46:47], v[46:47], v[162:163] op_sel_hi:[1,0]
	v_pk_mul_f32 v[40:41], v[40:41], v[162:163] op_sel_hi:[1,0]
	v_pk_mul_f32 v[42:43], v[42:43], v[162:163] op_sel_hi:[1,0]
	v_cvt_pk_bf16_f32 v36, v44, v45
	v_cvt_pk_bf16_f32 v37, v46, v47
	v_cvt_pk_bf16_f32 v38, v40, v41
	v_cvt_pk_bf16_f32 v39, v42, v43
	s_mov_b32 s100, 0xc6000
	v_lshl_add_u64 v[148:149], v[146:147], 0, s[100:101]
	global_store_dwordx4 v[148:149], v[36:39], off
	s_waitcnt vmcnt(7)
	v_cvt_f32_u32_e32 v166, v189
	v_cvt_f32_u32_e32 v167, v188
	v_fmamk_f32 v166, v166, 0x4f800000, v167
	v_fmamk_f32 v166, v166, 0x2a800000, v159
	v_rsq_f32_e32 v166, v166
	s_nop 0
	v_mul_f32_e32 v160, 0xbfb8aa3b, v166
	v_mul_f32_e32 v162, v166, v166
	v_pk_mul_f32 v[168:169], v[28:29], v[160:161] op_sel_hi:[1,0]
	v_pk_mul_f32 v[170:171], v[30:31], v[160:161] op_sel_hi:[1,0]
	v_pk_mul_f32 v[172:173], v[24:25], v[160:161] op_sel_hi:[1,0]
	v_pk_mul_f32 v[174:175], v[26:27], v[160:161] op_sel_hi:[1,0]
	v_exp_f32_e32 v168, v168
	v_exp_f32_e32 v169, v169
	v_exp_f32_e32 v170, v170
	v_exp_f32_e32 v171, v171
	v_exp_f32_e32 v172, v172
	v_exp_f32_e32 v173, v173
	v_exp_f32_e32 v174, v174
	v_exp_f32_e32 v175, v175
	v_pk_add_f32 v[168:169], v[168:169], v[164:165]
	v_pk_add_f32 v[170:171], v[170:171], v[164:165]
	v_pk_add_f32 v[172:173], v[172:173], v[164:165]
	v_pk_add_f32 v[174:175], v[174:175], v[164:165]
	v_rcp_f32_e32 v168, v168
	v_rcp_f32_e32 v169, v169
	v_rcp_f32_e32 v170, v170
	v_rcp_f32_e32 v171, v171
	v_rcp_f32_e32 v172, v172
	v_rcp_f32_e32 v173, v173
	v_rcp_f32_e32 v174, v174
	v_rcp_f32_e32 v175, v175
	v_pk_mul_f32 v[28:29], v[28:29], v[20:21]
	v_pk_mul_f32 v[30:31], v[30:31], v[22:23]
	v_pk_mul_f32 v[24:25], v[24:25], v[16:17]
	v_pk_mul_f32 v[26:27], v[26:27], v[18:19]
	v_pk_mul_f32 v[28:29], v[28:29], v[168:169]
	v_pk_mul_f32 v[30:31], v[30:31], v[170:171]
	v_pk_mul_f32 v[24:25], v[24:25], v[172:173]
	v_pk_mul_f32 v[26:27], v[26:27], v[174:175]
	v_pk_mul_f32 v[28:29], v[28:29], v[162:163] op_sel_hi:[1,0]
	v_pk_mul_f32 v[30:31], v[30:31], v[162:163] op_sel_hi:[1,0]
	v_pk_mul_f32 v[24:25], v[24:25], v[162:163] op_sel_hi:[1,0]
	v_pk_mul_f32 v[26:27], v[26:27], v[162:163] op_sel_hi:[1,0]
	v_cvt_pk_bf16_f32 v20, v28, v29
	v_cvt_pk_bf16_f32 v21, v30, v31
	v_cvt_pk_bf16_f32 v22, v24, v25
	v_cvt_pk_bf16_f32 v23, v26, v27
	s_mov_b32 s100, 0xdc000
	v_lshl_add_u64 v[148:149], v[146:147], 0, s[100:101]
	global_store_dwordx4 v[148:149], v[20:23], off
	s_waitcnt vmcnt(7)
	v_cvt_f32_u32_e32 v166, v191
	v_cvt_f32_u32_e32 v167, v190
	v_fmamk_f32 v166, v166, 0x4f800000, v167
	v_fmamk_f32 v166, v166, 0x2a800000, v159
	v_rsq_f32_e32 v166, v166
	s_nop 0
	v_mul_f32_e32 v160, 0xbfb8aa3b, v166
	v_mul_f32_e32 v162, v166, v166
	v_pk_mul_f32 v[168:169], v[12:13], v[160:161] op_sel_hi:[1,0]
	v_pk_mul_f32 v[170:171], v[14:15], v[160:161] op_sel_hi:[1,0]
	v_pk_mul_f32 v[172:173], v[8:9], v[160:161] op_sel_hi:[1,0]
	v_pk_mul_f32 v[174:175], v[10:11], v[160:161] op_sel_hi:[1,0]
	v_exp_f32_e32 v168, v168
	v_exp_f32_e32 v169, v169
	v_exp_f32_e32 v170, v170
	v_exp_f32_e32 v171, v171
	v_exp_f32_e32 v172, v172
	v_exp_f32_e32 v173, v173
	v_exp_f32_e32 v174, v174
	v_exp_f32_e32 v175, v175
	v_pk_add_f32 v[168:169], v[168:169], v[164:165]
	v_pk_add_f32 v[170:171], v[170:171], v[164:165]
	v_pk_add_f32 v[172:173], v[172:173], v[164:165]
	v_pk_add_f32 v[174:175], v[174:175], v[164:165]
	v_rcp_f32_e32 v168, v168
	v_rcp_f32_e32 v169, v169
	v_rcp_f32_e32 v170, v170
	v_rcp_f32_e32 v171, v171
	v_rcp_f32_e32 v172, v172
	v_rcp_f32_e32 v173, v173
	v_rcp_f32_e32 v174, v174
	v_rcp_f32_e32 v175, v175
	v_pk_mul_f32 v[12:13], v[12:13], v[4:5]
	v_pk_mul_f32 v[14:15], v[14:15], v[6:7]
	v_pk_mul_f32 v[8:9], v[8:9], v[0:1]
	v_pk_mul_f32 v[10:11], v[10:11], v[2:3]
	v_pk_mul_f32 v[12:13], v[12:13], v[168:169]
	v_pk_mul_f32 v[14:15], v[14:15], v[170:171]
	v_pk_mul_f32 v[8:9], v[8:9], v[172:173]
	v_pk_mul_f32 v[10:11], v[10:11], v[174:175]
	v_pk_mul_f32 v[12:13], v[12:13], v[162:163] op_sel_hi:[1,0]
	v_pk_mul_f32 v[14:15], v[14:15], v[162:163] op_sel_hi:[1,0]
	v_pk_mul_f32 v[8:9], v[8:9], v[162:163] op_sel_hi:[1,0]
	v_pk_mul_f32 v[10:11], v[10:11], v[162:163] op_sel_hi:[1,0]
	v_cvt_pk_bf16_f32 v4, v12, v13
	v_cvt_pk_bf16_f32 v5, v14, v15
	v_cvt_pk_bf16_f32 v6, v8, v9
	v_cvt_pk_bf16_f32 v7, v10, v11
	s_mov_b32 s100, 0xf2000
	v_lshl_add_u64 v[148:149], v[146:147], 0, s[100:101]
	global_store_dwordx4 v[148:149], v[4:7], off
	s_cbranch_vccnz .LBB0_845
	s_andn2_b64 vcc, exec, s[4:5]
	s_cbranch_vccnz .LBB0_844
	s_barrier
	s_branch .LBB0_844

; __device__ __forceinline__ float ss_scale(const u64* ss, int row) { return __builtin_amdgcn_rsqf((float)ss[row] * (1.f / 4294967296.f / 1024.f) + EPS); }
; __device__ __forceinline__ unsigned pkbf(float lo, float hi) { typedef __bf16 bf2_t __attribute__((ext_vector_type(2))); f32x2 v = {lo, hi}; bf2_t b = __builtin_convertvector(v, bf2_t); return __builtin_bit_cast(unsigned, b); }
; __device__ __forceinline__ float silu_f(float g) { return g * __builtin_amdgcn_rcpf(1.f + __builtin_amdgcn_exp2f(-g * LOG2E)); }
;     __device__ __forceinline__ void operator()(const f32x4 (&acc)[2][2][4][2], const pg8::Unit& u, int wr, int wc, int fr, int fq) const {
;         const int row0 = u.pm * 256 + wr * 64 + fr, col0 = u.pn * 128 + wc * 32 + 8 * fq;
; #pragma unroll
;         for (int ai = 0; ai < 2; ++ai)
; #pragma unroll
;             for (int m = 0; m < 4; ++m) {
;                 const int row = row0 + ai * 128 + m * 16;
;                 float s = ss_scale(ss, row);
;                 if constexpr (NN) s *= __builtin_amdgcn_rsqf(s * s * (float)ssw[row] * (1.f / 4294967296.f / 1024.f) + EPS);
;                 float a[8];
; #pragma unroll
;                 for (int n = 0; n < 2; ++n)
; #pragma unroll
;                     for (int i = 0; i < 4; ++i) { const float g = acc[ai][0][m][n][i] * s, uu = acc[ai][1][m][n][i] * s; a[4 * n + i] = silu_f(g) * uu; }
;                 u32x4 w; w.x = pkbf(a[0], a[1]); w.y = pkbf(a[2], a[3]); w.z = pkbf(a[4], a[5]); w.w = pkbf(a[6], a[7]);
;                 *(u32x4*)(O + (size_t)row * FF + col0) = w;
.LBB0_1010:
	v_lshl_add_u32 v144, s24, 8, v154
	v_mov_b32_e32 v145, 0
	v_lshl_add_u64 v[150:151], v[144:145], 3, s[8:9]
	global_load_dwordx2 v[176:177], v[150:151], off
	global_load_dwordx2 v[178:179], v[150:151], off offset:128
	global_load_dwordx2 v[180:181], v[150:151], off offset:256
	global_load_dwordx2 v[182:183], v[150:151], off offset:384
	global_load_dwordx2 v[184:185], v[150:151], off offset:1024
	global_load_dwordx2 v[186:187], v[150:151], off offset:1152
	global_load_dwordx2 v[188:189], v[150:151], off offset:1280
	global_load_dwordx2 v[190:191], v[150:151], off offset:1408
	v_lshl_add_u64 v[210:211], v[144:145], 3, s[10:11]
	global_load_dwordx2 v[192:193], v[210:211], off
	global_load_dwordx2 v[194:195], v[210:211], off offset:128
	global_load_dwordx2 v[196:197], v[210:211], off offset:256
	global_load_dwordx2 v[200:201], v[210:211], off offset:384
	global_load_dwordx2 v[202:203], v[210:211], off offset:1024
	global_load_dwordx2 v[204:205], v[210:211], off offset:1152
	global_load_dwordx2 v[206:207], v[210:211], off offset:1280
	global_load_dwordx2 v[208:209], v[210:211], off offset:1408
	v_lshl_or_b32 v148, s55, 7, v155
	v_mul_u32_u24_e32 v146, s54, v144
	v_lshl_add_u32 v146, v148, 1, v146
	v_mov_b32_e32 v147, 0
	v_lshl_add_u64 v[146:147], v[146:147], 0, s[6:7]
	v_mov_b32_e32 v164, 1.0
	v_mov_b32_e32 v165, 1.0
	s_andn2_b64 vcc, exec, s[2:3]
	s_mov_b64 s[2:3], -1
	s_mov_b32 s101, 0
	s_waitcnt vmcnt(7)
	v_cvt_f32_u32_e32 v166, v177
	v_cvt_f32_u32_e32 v167, v176
	v_fmamk_f32 v166, v166, 0x4f800000, v167
	v_fmamk_f32 v166, v166, 0x2a800000, v161
	v_rsq_f32_e32 v166, v166
	v_cvt_f32_u32_e32 v167, v193
	v_cvt_f32_u32_e32 v152, v192
	v_fmamk_f32 v167, v167, 0x4f800000, v152
	v_mul_f32_e32 v152, v166, v166
	v_mul_f32_e32 v152, v152, v167
	v_fmamk_f32 v152, v152, 0x2a800000, v161
	v_rsq_f32_e32 v152, v152
	s_nop 0
	v_mul_f32_e32 v166, v166, v152
	v_mul_f32_e32 v152, 0xbfb8aa3b, v166
	v_mul_f32_e32 v162, v166, v166
	v_pk_mul_f32 v[168:169], v[124:125], v[152:153] op_sel_hi:[1,0]
	v_pk_mul_f32 v[170:171], v[126:127], v[152:153] op_sel_hi:[1,0]
	v_pk_mul_f32 v[172:173], v[120:121], v[152:153] op_sel_hi:[1,0]
	v_pk_mul_f32 v[174:175], v[122:123], v[152:153] op_sel_hi:[1,0]
	v_exp_f32_e32 v168, v168
	v_exp_f32_e32 v169, v169
	v_exp_f32_e32 v170, v170
	v_exp_f32_e32 v171, v171
	v_exp_f32_e32 v172, v172
	v_exp_f32_e32 v173, v173
	v_exp_f32_e32 v174, v174
	v_exp_f32_e32 v175, v175
	v_pk_add_f32 v[168:169], v[168:169], v[164:165]
	v_pk_add_f32 v[170:171], v[170:171], v[164:165]
	v_pk_add_f32 v[172:173], v[172:173], v[164:165]
	v_pk_add_f32 v[174:175], v[174:175], v[164:165]
	v_rcp_f32_e32 v168, v168
	v_rcp_f32_e32 v169, v169
	v_rcp_f32_e32 v170, v170
	v_rcp_f32_e32 v171, v171
	v_rcp_f32_e32 v172, v172
	v_rcp_f32_e32 v173, v173
	v_rcp_f32_e32 v174, v174
	v_rcp_f32_e32 v175, v175
	v_pk_mul_f32 v[124:125], v[124:125], v[116:117]
	v_pk_mul_f32 v[126:127], v[126:127], v[118:119]
	v_pk_mul_f32 v[120:121], v[120:121], v[112:113]
	v_pk_mul_f32 v[122:123], v[122:123], v[114:115]
	v_pk_mul_f32 v[124:125], v[124:125], v[168:169]
	v_pk_mul_f32 v[126:127], v[126:127], v[170:171]
	v_pk_mul_f32 v[120:121], v[120:121], v[172:173]
	v_pk_mul_f32 v[122:123], v[122:123], v[174:175]
	v_pk_mul_f32 v[124:125], v[124:125], v[162:163] op_sel_hi:[1,0]
	v_pk_mul_f32 v[126:127], v[126:127], v[162:163] op_sel_hi:[1,0]
	v_pk_mul_f32 v[120:121], v[120:121], v[162:163] op_sel_hi:[1,0]
	v_pk_mul_f32 v[122:123], v[122:123], v[162:163] op_sel_hi:[1,0]
	v_cvt_pk_bf16_f32 v116, v124, v125
	v_cvt_pk_bf16_f32 v117, v126, v127
	v_cvt_pk_bf16_f32 v118, v120, v121
	v_cvt_pk_bf16_f32 v119, v122, v123
	global_store_dwordx4 v[146:147], v[116:119], off
	s_waitcnt vmcnt(7)
	v_cvt_f32_u32_e32 v166, v179
	v_cvt_f32_u32_e32 v167, v178
	v_fmamk_f32 v166, v166, 0x4f800000, v167
	v_fmamk_f32 v166, v166, 0x2a800000, v161
	v_rsq_f32_e32 v166, v166
	v_cvt_f32_u32_e32 v167, v195
	v_cvt_f32_u32_e32 v152, v194
	v_fmamk_f32 v167, v167, 0x4f800000, v152
	v_mul_f32_e32 v152, v166, v166
	v_mul_f32_e32 v152, v152, v167
	v_fmamk_f32 v152, v152, 0x2a800000, v161
	v_rsq_f32_e32 v152, v152
	s_nop 0
	v_mul_f32_e32 v166, v166, v152
	v_mul_f32_e32 v152, 0xbfb8aa3b, v166
	v_mul_f32_e32 v162, v166, v166
	v_pk_mul_f32 v[168:169], v[108:109], v[152:153] op_sel_hi:[1,0]
	v_pk_mul_f32 v[170:171], v[110:111], v[152:153] op_sel_hi:[1,0]
	v_pk_mul_f32 v[172:173], v[104:105], v[152:153] op_sel_hi:[1,0]
	v_pk_mul_f32 v[174:175], v[106:107], v[152:153] op_sel_hi:[1,0]
	v_exp_f32_e32 v168, v168
	v_exp_f32_e32 v169, v169
	v_exp_f32_e32 v170, v170
	v_exp_f32_e32 v171, v171
	v_exp_f32_e32 v172, v172
	v_exp_f32_e32 v173, v173
	v_exp_f32_e32 v174, v174
	v_exp_f32_e32 v175, v175
	v_pk_add_f32 v[168:169], v[168:169], v[164:165]
	v_pk_add_f32 v[170:171], v[170:171], v[164:165]
	v_pk_add_f32 v[172:173], v[172:173], v[164:165]
	v_pk_add_f32 v[174:175], v[174:175], v[164:165]
	v_rcp_f32_e32 v168, v168
	v_rcp_f32_e32 v169, v169
	v_rcp_f32_e32 v170, v170
	v_rcp_f32_e32 v171, v171
	v_rcp_f32_e32 v172, v172
	v_rcp_f32_e32 v173, v173
	v_rcp_f32_e32 v174, v174
	v_rcp_f32_e32 v175, v175
	v_pk_mul_f32 v[108:109], v[108:109], v[100:101]
	v_pk_mul_f32 v[110:111], v[110:111], v[102:103]
	v_pk_mul_f32 v[104:105], v[104:105], v[96:97]
	v_pk_mul_f32 v[106:107], v[106:107], v[98:99]
	v_pk_mul_f32 v[108:109], v[108:109], v[168:169]
	v_pk_mul_f32 v[110:111], v[110:111], v[170:171]
	v_pk_mul_f32 v[104:105], v[104:105], v[172:173]
	v_pk_mul_f32 v[106:107], v[106:107], v[174:175]
	v_pk_mul_f32 v[108:109], v[108:109], v[162:163] op_sel_hi:[1,0]
	v_pk_mul_f32 v[110:111], v[110:111], v[162:163] op_sel_hi:[1,0]
	v_pk_mul_f32 v[104:105], v[104:105], v[162:163] op_sel_hi:[1,0]
	v_pk_mul_f32 v[106:107], v[106:107], v[162:163] op_sel_hi:[1,0]
	v_cvt_pk_bf16_f32 v100, v108, v109
	v_cvt_pk_bf16_f32 v101, v110, v111
	v_cvt_pk_bf16_f32 v102, v104, v105
	v_cvt_pk_bf16_f32 v103, v106, v107
	s_mov_b32 s100, 0x16000
	v_lshl_add_u64 v[148:149], v[146:147], 0, s[100:101]
	global_store_dwordx4 v[148:149], v[100:103], off
	s_waitcnt vmcnt(7)
; __device__ __forceinline__ float ss_scale(const u64* ss, int row) { return __builtin_amdgcn_rsqf((float)ss[row] * (1.f / 4294967296.f / 1024.f) + EPS); }
; __device__ __forceinline__ unsigned pkbf(float lo, float hi) { typedef __bf16 bf2_t __attribute__((ext_vector_type(2))); f32x2 v = {lo, hi}; bf2_t b = __builtin_convertvector(v, bf2_t); return __builtin_bit_cast(unsigned, b); }
; __device__ __forceinline__ float silu_f(float g) { return g * __builtin_amdgcn_rcpf(1.f + __builtin_amdgcn_exp2f(-g * LOG2E)); }
;     __device__ __forceinline__ void operator()(const f32x4 (&acc)[2][2][4][2], const pg8::Unit& u, int wr, int wc, int fr, int fq) const {
;         const int row0 = u.pm * 256 + wr * 64 + fr, col0 = u.pn * 128 + wc * 32 + 8 * fq;
; #pragma unroll
;         for (int ai = 0; ai < 2; ++ai)
; #pragma unroll
;             for (int m = 0; m < 4; ++m) {
;                 const int row = row0 + ai * 128 + m * 16;
;                 float s = ss_scale(ss, row);
;                 if constexpr (NN) s *= __builtin_amdgcn_rsqf(s * s * (float)ssw[row] * (1.f / 4294967296.f / 1024.f) + EPS);
;                 float a[8];
; #pragma unroll
;                 for (int n = 0; n < 2; ++n)
; #pragma unroll
;                     for (int i = 0; i < 4; ++i) { const float g = acc[ai][0][m][n][i] * s, uu = acc[ai][1][m][n][i] * s; a[4 * n + i] = silu_f(g) * uu; }
;                 u32x4 w; w.x = pkbf(a[0], a[1]); w.y = pkbf(a[2], a[3]); w.z = pkbf(a[4], a[5]); w.w = pkbf(a[6], a[7]);
;                 *(u32x4*)(O + (size_t)row * FF + col0) = w;
	v_cvt_f32_u32_e32 v166, v181
	v_cvt_f32_u32_e32 v167, v180
	v_fmamk_f32 v166, v166, 0x4f800000, v167
	v_fmamk_f32 v166, v166, 0x2a800000, v161
	v_rsq_f32_e32 v166, v166
	v_cvt_f32_u32_e32 v167, v197
	v_cvt_f32_u32_e32 v152, v196
	v_fmamk_f32 v167, v167, 0x4f800000, v152
	v_mul_f32_e32 v152, v166, v166
	v_mul_f32_e32 v152, v152, v167
	v_fmamk_f32 v152, v152, 0x2a800000, v161
	v_rsq_f32_e32 v152, v152
	s_nop 0
	v_mul_f32_e32 v166, v166, v152
	v_mul_f32_e32 v152, 0xbfb8aa3b, v166
	v_mul_f32_e32 v162, v166, v166
	v_pk_mul_f32 v[168:169], v[92:93], v[152:153] op_sel_hi:[1,0]
	v_pk_mul_f32 v[170:171], v[94:95], v[152:153] op_sel_hi:[1,0]
	v_pk_mul_f32 v[172:173], v[88:89], v[152:153] op_sel_hi:[1,0]
	v_pk_mul_f32 v[174:175], v[90:91], v[152:153] op_sel_hi:[1,0]
	v_exp_f32_e32 v168, v168
	v_exp_f32_e32 v169, v169
	v_exp_f32_e32 v170, v170
	v_exp_f32_e32 v171, v171
	v_exp_f32_e32 v172, v172
	v_exp_f32_e32 v173, v173
	v_exp_f32_e32 v174, v174
	v_exp_f32_e32 v175, v175
	v_pk_add_f32 v[168:169], v[168:169], v[164:165]
	v_pk_add_f32 v[170:171], v[170:171], v[164:165]
	v_pk_add_f32 v[172:173], v[172:173], v[164:165]
	v_pk_add_f32 v[174:175], v[174:175], v[164:165]
	v_rcp_f32_e32 v168, v168
	v_rcp_f32_e32 v169, v169
	v_rcp_f32_e32 v170, v170
	v_rcp_f32_e32 v171, v171
	v_rcp_f32_e32 v172, v172
	v_rcp_f32_e32 v173, v173
	v_rcp_f32_e32 v174, v174
	v_rcp_f32_e32 v175, v175
	v_pk_mul_f32 v[92:93], v[92:93], v[84:85]
	v_pk_mul_f32 v[94:95], v[94:95], v[86:87]
	v_pk_mul_f32 v[88:89], v[88:89], v[80:81]
	v_pk_mul_f32 v[90:91], v[90:91], v[82:83]
	v_pk_mul_f32 v[92:93], v[92:93], v[168:169]
	v_pk_mul_f32 v[94:95], v[94:95], v[170:171]
	v_pk_mul_f32 v[88:89], v[88:89], v[172:173]
	v_pk_mul_f32 v[90:91], v[90:91], v[174:175]
	v_pk_mul_f32 v[92:93], v[92:93], v[162:163] op_sel_hi:[1,0]
	v_pk_mul_f32 v[94:95], v[94:95], v[162:163] op_sel_hi:[1,0]
	v_pk_mul_f32 v[88:89], v[88:89], v[162:163] op_sel_hi:[1,0]
	v_pk_mul_f32 v[90:91], v[90:91], v[162:163] op_sel_hi:[1,0]
	v_cvt_pk_bf16_f32 v84, v92, v93
	v_cvt_pk_bf16_f32 v85, v94, v95
	v_cvt_pk_bf16_f32 v86, v88, v89
	v_cvt_pk_bf16_f32 v87, v90, v91
	s_mov_b32 s100, 0x2c000
	v_lshl_add_u64 v[148:149], v[146:147], 0, s[100:101]
	global_store_dwordx4 v[148:149], v[84:87], off
	s_waitcnt vmcnt(7)
	v_cvt_f32_u32_e32 v166, v183
	v_cvt_f32_u32_e32 v167, v182
	v_fmamk_f32 v166, v166, 0x4f800000, v167
	v_fmamk_f32 v166, v166, 0x2a800000, v161
	v_rsq_f32_e32 v166, v166
	v_cvt_f32_u32_e32 v167, v201
	v_cvt_f32_u32_e32 v152, v200
	v_fmamk_f32 v167, v167, 0x4f800000, v152
	v_mul_f32_e32 v152, v166, v166
	v_mul_f32_e32 v152, v152, v167
	v_fmamk_f32 v152, v152, 0x2a800000, v161
	v_rsq_f32_e32 v152, v152
	s_nop 0
	v_mul_f32_e32 v166, v166, v152
	v_mul_f32_e32 v152, 0xbfb8aa3b, v166
	v_mul_f32_e32 v162, v166, v166
	v_pk_mul_f32 v[168:169], v[76:77], v[152:153] op_sel_hi:[1,0]
	v_pk_mul_f32 v[170:171], v[78:79], v[152:153] op_sel_hi:[1,0]
	v_pk_mul_f32 v[172:173], v[72:73], v[152:153] op_sel_hi:[1,0]
	v_pk_mul_f32 v[174:175], v[74:75], v[152:153] op_sel_hi:[1,0]
	v_exp_f32_e32 v168, v168
	v_exp_f32_e32 v169, v169
	v_exp_f32_e32 v170, v170
	v_exp_f32_e32 v171, v171
	v_exp_f32_e32 v172, v172
	v_exp_f32_e32 v173, v173
	v_exp_f32_e32 v174, v174
	v_exp_f32_e32 v175, v175
	v_pk_add_f32 v[168:169], v[168:169], v[164:165]
	v_pk_add_f32 v[170:171], v[170:171], v[164:165]
	v_pk_add_f32 v[172:173], v[172:173], v[164:165]
	v_pk_add_f32 v[174:175], v[174:175], v[164:165]
	v_rcp_f32_e32 v168, v168
	v_rcp_f32_e32 v169, v169
	v_rcp_f32_e32 v170, v170
	v_rcp_f32_e32 v171, v171
	v_rcp_f32_e32 v172, v172
	v_rcp_f32_e32 v173, v173
	v_rcp_f32_e32 v174, v174
	v_rcp_f32_e32 v175, v175
	v_pk_mul_f32 v[76:77], v[76:77], v[68:69]
	v_pk_mul_f32 v[78:79], v[78:79], v[70:71]
	v_pk_mul_f32 v[72:73], v[72:73], v[64:65]
	v_pk_mul_f32 v[74:75], v[74:75], v[66:67]
	v_pk_mul_f32 v[76:77], v[76:77], v[168:169]
	v_pk_mul_f32 v[78:79], v[78:79], v[170:171]
	v_pk_mul_f32 v[72:73], v[72:73], v[172:173]
	v_pk_mul_f32 v[74:75], v[74:75], v[174:175]
	v_pk_mul_f32 v[76:77], v[76:77], v[162:163] op_sel_hi:[1,0]
	v_pk_mul_f32 v[78:79], v[78:79], v[162:163] op_sel_hi:[1,0]
	v_pk_mul_f32 v[72:73], v[72:73], v[162:163] op_sel_hi:[1,0]
	v_pk_mul_f32 v[74:75], v[74:75], v[162:163] op_sel_hi:[1,0]
	v_cvt_pk_bf16_f32 v68, v76, v77
	v_cvt_pk_bf16_f32 v69, v78, v79
	v_cvt_pk_bf16_f32 v70, v72, v73
	v_cvt_pk_bf16_f32 v71, v74, v75
	s_mov_b32 s100, 0x42000
	v_lshl_add_u64 v[148:149], v[146:147], 0, s[100:101]
	global_store_dwordx4 v[148:149], v[68:71], off
	s_waitcnt vmcnt(7)
	v_cvt_f32_u32_e32 v166, v185
	v_cvt_f32_u32_e32 v167, v184
	v_fmamk_f32 v166, v166, 0x4f800000, v167
	v_fmamk_f32 v166, v166, 0x2a800000, v161
	v_rsq_f32_e32 v166, v166
	v_cvt_f32_u32_e32 v167, v203
	v_cvt_f32_u32_e32 v152, v202
	v_fmamk_f32 v167, v167, 0x4f800000, v152
	v_mul_f32_e32 v152, v166, v166
	v_mul_f32_e32 v152, v152, v167
	v_fmamk_f32 v152, v152, 0x2a800000, v161
	v_rsq_f32_e32 v152, v152
	s_nop 0
	v_mul_f32_e32 v166, v166, v152
	v_mul_f32_e32 v152, 0xbfb8aa3b, v166
	v_mul_f32_e32 v162, v166, v166
	v_pk_mul_f32 v[168:169], v[60:61], v[152:153] op_sel_hi:[1,0]
	v_pk_mul_f32 v[170:171], v[62:63], v[152:153] op_sel_hi:[1,0]
	v_pk_mul_f32 v[172:173], v[56:57], v[152:153] op_sel_hi:[1,0]
	v_pk_mul_f32 v[174:175], v[58:59], v[152:153] op_sel_hi:[1,0]
	v_exp_f32_e32 v168, v168
	v_exp_f32_e32 v169, v169
	v_exp_f32_e32 v170, v170
	v_exp_f32_e32 v171, v171
	v_exp_f32_e32 v172, v172
	v_exp_f32_e32 v173, v173
	v_exp_f32_e32 v174, v174
	v_exp_f32_e32 v175, v175
	v_pk_add_f32 v[168:169], v[168:169], v[164:165]
	v_pk_add_f32 v[170:171], v[170:171], v[164:165]
	v_pk_add_f32 v[172:173], v[172:173], v[164:165]
	v_pk_add_f32 v[174:175], v[174:175], v[164:165]
	v_rcp_f32_e32 v168, v168
	v_rcp_f32_e32 v169, v169
	v_rcp_f32_e32 v170, v170
	v_rcp_f32_e32 v171, v171
	v_rcp_f32_e32 v172, v172
	v_rcp_f32_e32 v173, v173
	v_rcp_f32_e32 v174, v174
	v_rcp_f32_e32 v175, v175
	v_pk_mul_f32 v[60:61], v[60:61], v[52:53]
	v_pk_mul_f32 v[62:63], v[62:63], v[54:55]
	v_pk_mul_f32 v[56:57], v[56:57], v[48:49]
	v_pk_mul_f32 v[58:59], v[58:59], v[50:51]
	v_pk_mul_f32 v[60:61], v[60:61], v[168:169]
	v_pk_mul_f32 v[62:63], v[62:63], v[170:171]
	v_pk_mul_f32 v[56:57], v[56:57], v[172:173]
	v_pk_mul_f32 v[58:59], v[58:59], v[174:175]
	v_pk_mul_f32 v[60:61], v[60:61], v[162:163] op_sel_hi:[1,0]
	v_pk_mul_f32 v[62:63], v[62:63], v[162:163] op_sel_hi:[1,0]
	v_pk_mul_f32 v[56:57], v[56:57], v[162:163] op_sel_hi:[1,0]
	v_pk_mul_f32 v[58:59], v[58:59], v[162:163] op_sel_hi:[1,0]
	v_cvt_pk_bf16_f32 v52, v60, v61
	v_cvt_pk_bf16_f32 v53, v62, v63
	v_cvt_pk_bf16_f32 v54, v56, v57
	v_cvt_pk_bf16_f32 v55, v58, v59
	s_mov_b32 s100, 0xb0000
	v_lshl_add_u64 v[148:149], v[146:147], 0, s[100:101]
	global_store_dwordx4 v[148:149], v[52:55], off
	s_waitcnt vmcnt(7)
; __device__ __forceinline__ float ss_scale(const u64* ss, int row) { return __builtin_amdgcn_rsqf((float)ss[row] * (1.f / 4294967296.f / 1024.f) + EPS); }
; __device__ __forceinline__ unsigned pkbf(float lo, float hi) { typedef __bf16 bf2_t __attribute__((ext_vector_type(2))); f32x2 v = {lo, hi}; bf2_t b = __builtin_convertvector(v, bf2_t); return __builtin_bit_cast(unsigned, b); }
; __device__ __forceinline__ float silu_f(float g) { return g * __builtin_amdgcn_rcpf(1.f + __builtin_amdgcn_exp2f(-g * LOG2E)); }
;     __device__ __forceinline__ void operator()(const f32x4 (&acc)[2][2][4][2], const pg8::Unit& u, int wr, int wc, int fr, int fq) const {
;         const int row0 = u.pm * 256 + wr * 64 + fr, col0 = u.pn * 128 + wc * 32 + 8 * fq;
; #pragma unroll
;         for (int ai = 0; ai < 2; ++ai)
; #pragma unroll
;             for (int m = 0; m < 4; ++m) {
;                 const int row = row0 + ai * 128 + m * 16;
;                 float s = ss_scale(ss, row);
;                 if constexpr (NN) s *= __builtin_amdgcn_rsqf(s * s * (float)ssw[row] * (1.f / 4294967296.f / 1024.f) + EPS);
;                 float a[8];
; #pragma unroll
;                 for (int n = 0; n < 2; ++n)
; #pragma unroll
;                     for (int i = 0; i < 4; ++i) { const float g = acc[ai][0][m][n][i] * s, uu = acc[ai][1][m][n][i] * s; a[4 * n + i] = silu_f(g) * uu; }
;                 u32x4 w; w.x = pkbf(a[0], a[1]); w.y = pkbf(a[2], a[3]); w.z = pkbf(a[4], a[5]); w.w = pkbf(a[6], a[7]);
;                 *(u32x4*)(O + (size_t)row * FF + col0) = w;
	v_cvt_f32_u32_e32 v166, v187
	v_cvt_f32_u32_e32 v167, v186
	v_fmamk_f32 v166, v166, 0x4f800000, v167
	v_fmamk_f32 v166, v166, 0x2a800000, v161
	v_rsq_f32_e32 v166, v166
	v_cvt_f32_u32_e32 v167, v205
	v_cvt_f32_u32_e32 v152, v204
	v_fmamk_f32 v167, v167, 0x4f800000, v152
	v_mul_f32_e32 v152, v166, v166
	v_mul_f32_e32 v152, v152, v167
	v_fmamk_f32 v152, v152, 0x2a800000, v161
	v_rsq_f32_e32 v152, v152
	s_nop 0
	v_mul_f32_e32 v166, v166, v152
	v_mul_f32_e32 v152, 0xbfb8aa3b, v166
	v_mul_f32_e32 v162, v166, v166
	v_pk_mul_f32 v[168:169], v[44:45], v[152:153] op_sel_hi:[1,0]
	v_pk_mul_f32 v[170:171], v[46:47], v[152:153] op_sel_hi:[1,0]
	v_pk_mul_f32 v[172:173], v[40:41], v[152:153] op_sel_hi:[1,0]
	v_pk_mul_f32 v[174:175], v[42:43], v[152:153] op_sel_hi:[1,0]
	v_exp_f32_e32 v168, v168
	v_exp_f32_e32 v169, v169
	v_exp_f32_e32 v170, v170
	v_exp_f32_e32 v171, v171
	v_exp_f32_e32 v172, v172
	v_exp_f32_e32 v173, v173
	v_exp_f32_e32 v174, v174
	v_exp_f32_e32 v175, v175
	v_pk_add_f32 v[168:169], v[168:169], v[164:165]
	v_pk_add_f32 v[170:171], v[170:171], v[164:165]
	v_pk_add_f32 v[172:173], v[172:173], v[164:165]
	v_pk_add_f32 v[174:175], v[174:175], v[164:165]
	v_rcp_f32_e32 v168, v168
	v_rcp_f32_e32 v169, v169
	v_rcp_f32_e32 v170, v170
	v_rcp_f32_e32 v171, v171
	v_rcp_f32_e32 v172, v172
	v_rcp_f32_e32 v173, v173
	v_rcp_f32_e32 v174, v174
	v_rcp_f32_e32 v175, v175
	v_pk_mul_f32 v[44:45], v[44:45], v[36:37]
	v_pk_mul_f32 v[46:47], v[46:47], v[38:39]
	v_pk_mul_f32 v[40:41], v[40:41], v[32:33]
	v_pk_mul_f32 v[42:43], v[42:43], v[34:35]
	v_pk_mul_f32 v[44:45], v[44:45], v[168:169]
	v_pk_mul_f32 v[46:47], v[46:47], v[170:171]
	v_pk_mul_f32 v[40:41], v[40:41], v[172:173]
	v_pk_mul_f32 v[42:43], v[42:43], v[174:175]
	v_pk_mul_f32 v[44:45], v[44:45], v[162:163] op_sel_hi:[1,0]
	v_pk_mul_f32 v[46:47], v[46:47], v[162:163] op_sel_hi:[1,0]
	v_pk_mul_f32 v[40:41], v[40:41], v[162:163] op_sel_hi:[1,0]
	v_pk_mul_f32 v[42:43], v[42:43], v[162:163] op_sel_hi:[1,0]
	v_cvt_pk_bf16_f32 v36, v44, v45
	v_cvt_pk_bf16_f32 v37, v46, v47
	v_cvt_pk_bf16_f32 v38, v40, v41
	v_cvt_pk_bf16_f32 v39, v42, v43
	s_mov_b32 s100, 0xc6000
	v_lshl_add_u64 v[148:149], v[146:147], 0, s[100:101]
	global_store_dwordx4 v[148:149], v[36:39], off
	s_waitcnt vmcnt(7)
	v_cvt_f32_u32_e32 v166, v189
	v_cvt_f32_u32_e32 v167, v188
	v_fmamk_f32 v166, v166, 0x4f800000, v167
	v_fmamk_f32 v166, v166, 0x2a800000, v161
	v_rsq_f32_e32 v166, v166
	v_cvt_f32_u32_e32 v167, v207
	v_cvt_f32_u32_e32 v152, v206
	v_fmamk_f32 v167, v167, 0x4f800000, v152
	v_mul_f32_e32 v152, v166, v166
	v_mul_f32_e32 v152, v152, v167
	v_fmamk_f32 v152, v152, 0x2a800000, v161
	v_rsq_f32_e32 v152, v152
	s_nop 0
	v_mul_f32_e32 v166, v166, v152
	v_mul_f32_e32 v152, 0xbfb8aa3b, v166
	v_mul_f32_e32 v162, v166, v166
	v_pk_mul_f32 v[168:169], v[28:29], v[152:153] op_sel_hi:[1,0]
	v_pk_mul_f32 v[170:171], v[30:31], v[152:153] op_sel_hi:[1,0]
	v_pk_mul_f32 v[172:173], v[24:25], v[152:153] op_sel_hi:[1,0]
	v_pk_mul_f32 v[174:175], v[26:27], v[152:153] op_sel_hi:[1,0]
	v_exp_f32_e32 v168, v168
	v_exp_f32_e32 v169, v169
	v_exp_f32_e32 v170, v170
	v_exp_f32_e32 v171, v171
	v_exp_f32_e32 v172, v172
	v_exp_f32_e32 v173, v173
	v_exp_f32_e32 v174, v174
	v_exp_f32_e32 v175, v175
	v_pk_add_f32 v[168:169], v[168:169], v[164:165]
	v_pk_add_f32 v[170:171], v[170:171], v[164:165]
	v_pk_add_f32 v[172:173], v[172:173], v[164:165]
	v_pk_add_f32 v[174:175], v[174:175], v[164:165]
	v_rcp_f32_e32 v168, v168
	v_rcp_f32_e32 v169, v169
	v_rcp_f32_e32 v170, v170
	v_rcp_f32_e32 v171, v171
	v_rcp_f32_e32 v172, v172
	v_rcp_f32_e32 v173, v173
	v_rcp_f32_e32 v174, v174
	v_rcp_f32_e32 v175, v175
	v_pk_mul_f32 v[28:29], v[28:29], v[20:21]
	v_pk_mul_f32 v[30:31], v[30:31], v[22:23]
	v_pk_mul_f32 v[24:25], v[24:25], v[16:17]
	v_pk_mul_f32 v[26:27], v[26:27], v[18:19]
	v_pk_mul_f32 v[28:29], v[28:29], v[168:169]
	v_pk_mul_f32 v[30:31], v[30:31], v[170:171]
	v_pk_mul_f32 v[24:25], v[24:25], v[172:173]
	v_pk_mul_f32 v[26:27], v[26:27], v[174:175]
	v_pk_mul_f32 v[28:29], v[28:29], v[162:163] op_sel_hi:[1,0]
	v_pk_mul_f32 v[30:31], v[30:31], v[162:163] op_sel_hi:[1,0]
	v_pk_mul_f32 v[24:25], v[24:25], v[162:163] op_sel_hi:[1,0]
	v_pk_mul_f32 v[26:27], v[26:27], v[162:163] op_sel_hi:[1,0]
	v_cvt_pk_bf16_f32 v20, v28, v29
	v_cvt_pk_bf16_f32 v21, v30, v31
	v_cvt_pk_bf16_f32 v22, v24, v25
	v_cvt_pk_bf16_f32 v23, v26, v27
	s_mov_b32 s100, 0xdc000
	v_lshl_add_u64 v[148:149], v[146:147], 0, s[100:101]
	global_store_dwordx4 v[148:149], v[20:23], off
	s_waitcnt vmcnt(7)
	v_cvt_f32_u32_e32 v166, v191
	v_cvt_f32_u32_e32 v167, v190
	v_fmamk_f32 v166, v166, 0x4f800000, v167
	v_fmamk_f32 v166, v166, 0x2a800000, v161
	v_rsq_f32_e32 v166, v166
	v_cvt_f32_u32_e32 v167, v209
	v_cvt_f32_u32_e32 v152, v208
	v_fmamk_f32 v167, v167, 0x4f800000, v152
	v_mul_f32_e32 v152, v166, v166
	v_mul_f32_e32 v152, v152, v167
	v_fmamk_f32 v152, v152, 0x2a800000, v161
	v_rsq_f32_e32 v152, v152
	s_nop 0
	v_mul_f32_e32 v166, v166, v152
	v_mul_f32_e32 v152, 0xbfb8aa3b, v166
	v_mul_f32_e32 v162, v166, v166
	v_pk_mul_f32 v[168:169], v[12:13], v[152:153] op_sel_hi:[1,0]
	v_pk_mul_f32 v[170:171], v[14:15], v[152:153] op_sel_hi:[1,0]
	v_pk_mul_f32 v[172:173], v[8:9], v[152:153] op_sel_hi:[1,0]
	v_pk_mul_f32 v[174:175], v[10:11], v[152:153] op_sel_hi:[1,0]
	v_exp_f32_e32 v168, v168
	v_exp_f32_e32 v169, v169
	v_exp_f32_e32 v170, v170
	v_exp_f32_e32 v171, v171
	v_exp_f32_e32 v172, v172
	v_exp_f32_e32 v173, v173
	v_exp_f32_e32 v174, v174
	v_exp_f32_e32 v175, v175
	v_pk_add_f32 v[168:169], v[168:169], v[164:165]
	v_pk_add_f32 v[170:171], v[170:171], v[164:165]
	v_pk_add_f32 v[172:173], v[172:173], v[164:165]
	v_pk_add_f32 v[174:175], v[174:175], v[164:165]
	v_rcp_f32_e32 v168, v168
	v_rcp_f32_e32 v169, v169
	v_rcp_f32_e32 v170, v170
	v_rcp_f32_e32 v171, v171
	v_rcp_f32_e32 v172, v172
	v_rcp_f32_e32 v173, v173
	v_rcp_f32_e32 v174, v174
	v_rcp_f32_e32 v175, v175
	v_pk_mul_f32 v[12:13], v[12:13], v[4:5]
	v_pk_mul_f32 v[14:15], v[14:15], v[6:7]
	v_pk_mul_f32 v[8:9], v[8:9], v[0:1]
	v_pk_mul_f32 v[10:11], v[10:11], v[2:3]
	v_pk_mul_f32 v[12:13], v[12:13], v[168:169]
	v_pk_mul_f32 v[14:15], v[14:15], v[170:171]
	v_pk_mul_f32 v[8:9], v[8:9], v[172:173]
	v_pk_mul_f32 v[10:11], v[10:11], v[174:175]
	v_pk_mul_f32 v[12:13], v[12:13], v[162:163] op_sel_hi:[1,0]
	v_pk_mul_f32 v[14:15], v[14:15], v[162:163] op_sel_hi:[1,0]
	v_pk_mul_f32 v[8:9], v[8:9], v[162:163] op_sel_hi:[1,0]
	v_pk_mul_f32 v[10:11], v[10:11], v[162:163] op_sel_hi:[1,0]
	v_cvt_pk_bf16_f32 v4, v12, v13
	v_cvt_pk_bf16_f32 v5, v14, v15
	v_cvt_pk_bf16_f32 v6, v8, v9
	v_cvt_pk_bf16_f32 v7, v10, v11
	s_mov_b32 s100, 0xf2000
	v_lshl_add_u64 v[148:149], v[146:147], 0, s[100:101]
	global_store_dwordx4 v[148:149], v[4:7], off
	s_cbranch_vccnz .LBB0_1003
	s_andn2_b64 vcc, exec, s[4:5]
	s_cbranch_vccnz .LBB0_1002
	s_barrier
	s_branch .LBB0_1002
